# GLA chunk-local unit: prefix-sum ds_bpermute steps of 19 dimensions issued in groups, gate mat-vec LDS reads software-pipelined (alone, on the baseline)
# baseline (speedup 1.0000x reference)
; #define LAS __attribute__((address_space(3)))
; #define WSYNC() asm volatile("s_waitcnt lgkmcnt(0)" ::: "memory")
; __device__ __forceinline__ void gla_gates(const bf16* prow, const float* wg, const float* bg, int h, int lane, float (&bc)[32], LAS float* Wst) {
;     ...
;     float glr[16]; unpack8(*(const u32x4*)(prow + C_GLR), glr); unpack8(*(const u32x4*)(prow + C_GLR + 8), glr + 8);
;     WSYNC();
; #pragma unroll
;     for (int d4 = 0; d4 < 8; ++d4) { f32x4 z = *(const LAS f32x4*)(Wst + 512 + 4 * d4);
; #pragma unroll
;         for (int r = 0; r < 16; ++r) { const f32x4 w = *(const LAS f32x4*)(Wst + r * 32 + 4 * d4); z += w * glr[r]; }
.LBB0_439:
	s_or_b64 exec, exec, s[18:19]
	v_lshl_add_u64 v[54:55], v[50:51], 0, s[42:43]
	v_add_co_u32_e32 v50, vcc, s39, v50
	v_mov_b32_e32 v103, s61
	s_nop 0
	v_addc_co_u32_e32 v51, vcc, 0, v51, vcc
	global_load_dwordx4 v[50:53], v[50:51], off offset:512
	s_nop 0
	global_load_dwordx4 v[54:57], v[54:55], off offset:16
	s_waitcnt lgkmcnt(0)
	s_waitcnt vmcnt(1)
	v_lshlrev_b32_e32 v94, 16, v50
	v_and_b32_e32 v92, 0xffff0000, v50
	v_lshlrev_b32_e32 v90, 16, v51
	v_and_b32_e32 v88, 0xffff0000, v51
	v_lshlrev_b32_e32 v86, 16, v52
	v_and_b32_e32 v84, 0xffff0000, v52
	v_lshlrev_b32_e32 v82, 16, v53
	v_and_b32_e32 v80, 0xffff0000, v53
	s_waitcnt vmcnt(0)
	v_lshlrev_b32_e32 v78, 16, v54
	v_and_b32_e32 v76, 0xffff0000, v54
	v_lshlrev_b32_e32 v74, 16, v55
	v_and_b32_e32 v72, 0xffff0000, v55
	v_lshlrev_b32_e32 v70, 16, v56
	v_and_b32_e32 v68, 0xffff0000, v56
	v_lshlrev_b32_e32 v66, 16, v57
	v_and_b32_e32 v64, 0xffff0000, v57
	ds_read_b128 v[96:99], v103 offset:6400
	ds_read_b128 v[104:107], v103 offset:4352
	ds_read_b128 v[58:61], v103 offset:4368
	ds_read_b128 v[54:57], v103 offset:4384
	ds_read_b128 v[50:53], v103 offset:4400
	ds_read_b128 v[112:115], v103 offset:6448
	s_waitcnt lgkmcnt(4)
	v_pk_fma_f32 v[100:101], v[104:105], v[94:95], v[96:97] op_sel_hi:[1,0,1]
	v_pk_fma_f32 v[104:105], v[106:107], v[94:95], v[98:99] op_sel_hi:[1,0,1]
	ds_read_b128 v[96:99], v103 offset:4480
	s_waitcnt lgkmcnt(0)
	v_pk_fma_f32 v[104:105], v[92:93], v[98:99], v[104:105] op_sel_hi:[0,1,1]
	v_pk_fma_f32 v[100:101], v[92:93], v[96:97], v[100:101] op_sel_hi:[0,1,1]
	ds_read_b128 v[96:99], v103 offset:4608
	s_waitcnt lgkmcnt(0)
	v_pk_fma_f32 v[100:101], v[90:91], v[96:97], v[100:101] op_sel_hi:[0,1,1]
	v_pk_fma_f32 v[104:105], v[90:91], v[98:99], v[104:105] op_sel_hi:[0,1,1]
	ds_read_b128 v[96:99], v103 offset:4736
	s_waitcnt lgkmcnt(0)
	v_pk_fma_f32 v[104:105], v[88:89], v[98:99], v[104:105] op_sel_hi:[0,1,1]
	v_pk_fma_f32 v[100:101], v[88:89], v[96:97], v[100:101] op_sel_hi:[0,1,1]
	ds_read_b128 v[96:99], v103 offset:4864
	s_waitcnt lgkmcnt(0)
	v_pk_fma_f32 v[100:101], v[86:87], v[96:97], v[100:101] op_sel_hi:[0,1,1]
	v_pk_fma_f32 v[104:105], v[86:87], v[98:99], v[104:105] op_sel_hi:[0,1,1]
	ds_read_b128 v[96:99], v103 offset:4992
	s_waitcnt lgkmcnt(0)
	v_pk_fma_f32 v[104:105], v[84:85], v[98:99], v[104:105] op_sel_hi:[0,1,1]
	v_pk_fma_f32 v[100:101], v[84:85], v[96:97], v[100:101] op_sel_hi:[0,1,1]
	ds_read_b128 v[96:99], v103 offset:5120
	s_waitcnt lgkmcnt(0)
	v_pk_fma_f32 v[100:101], v[82:83], v[96:97], v[100:101] op_sel_hi:[0,1,1]
	v_pk_fma_f32 v[104:105], v[82:83], v[98:99], v[104:105] op_sel_hi:[0,1,1]
	ds_read_b128 v[96:99], v103 offset:5248
	s_waitcnt lgkmcnt(0)
	v_pk_fma_f32 v[104:105], v[80:81], v[98:99], v[104:105] op_sel_hi:[0,1,1]
	v_pk_fma_f32 v[100:101], v[80:81], v[96:97], v[100:101] op_sel_hi:[0,1,1]
	ds_read_b128 v[96:99], v103 offset:5376
	s_waitcnt lgkmcnt(0)
	v_pk_fma_f32 v[100:101], v[78:79], v[96:97], v[100:101] op_sel_hi:[0,1,1]
	v_pk_fma_f32 v[104:105], v[78:79], v[98:99], v[104:105] op_sel_hi:[0,1,1]
	ds_read_b128 v[96:99], v103 offset:5504
	s_waitcnt lgkmcnt(0)
	v_pk_fma_f32 v[104:105], v[76:77], v[98:99], v[104:105] op_sel_hi:[0,1,1]
	v_pk_fma_f32 v[100:101], v[76:77], v[96:97], v[100:101] op_sel_hi:[0,1,1]
	ds_read_b128 v[96:99], v103 offset:5632
	s_waitcnt lgkmcnt(0)
	v_pk_fma_f32 v[100:101], v[74:75], v[96:97], v[100:101] op_sel_hi:[0,1,1]
	v_pk_fma_f32 v[104:105], v[74:75], v[98:99], v[104:105] op_sel_hi:[0,1,1]
	ds_read_b128 v[96:99], v103 offset:5760
	s_waitcnt lgkmcnt(0)
	v_pk_fma_f32 v[104:105], v[72:73], v[98:99], v[104:105] op_sel_hi:[0,1,1]
	v_pk_fma_f32 v[100:101], v[72:73], v[96:97], v[100:101] op_sel_hi:[0,1,1]
	ds_read_b128 v[96:99], v103 offset:5888
	s_waitcnt lgkmcnt(0)
	v_pk_fma_f32 v[100:101], v[70:71], v[96:97], v[100:101] op_sel_hi:[0,1,1]
	v_pk_fma_f32 v[104:105], v[70:71], v[98:99], v[104:105] op_sel_hi:[0,1,1]
	ds_read_b128 v[96:99], v103 offset:6016
	s_waitcnt lgkmcnt(0)
	v_pk_fma_f32 v[104:105], v[68:69], v[98:99], v[104:105] op_sel_hi:[0,1,1]
	v_pk_fma_f32 v[100:101], v[68:69], v[96:97], v[100:101] op_sel_hi:[0,1,1]
	ds_read_b128 v[96:99], v103 offset:6144
	s_waitcnt lgkmcnt(0)
	v_pk_fma_f32 v[100:101], v[66:67], v[96:97], v[100:101] op_sel_hi:[0,1,1]
	v_pk_fma_f32 v[104:105], v[66:67], v[98:99], v[104:105] op_sel_hi:[0,1,1]
	ds_read_b128 v[96:99], v103 offset:6272
	s_waitcnt lgkmcnt(0)
; #define LAS __attribute__((address_space(3)))
; __device__ __forceinline__ void gla_gates(const bf16* prow, const float* wg, const float* bg, int h, int lane, float (&bc)[32], LAS float* Wst) {
;     ...
;     for (int d4 = 0; d4 < 8; ++d4) { f32x4 z = *(const LAS f32x4*)(Wst + 512 + 4 * d4);
; #pragma unroll
;         for (int r = 0; r < 16; ++r) { const f32x4 w = *(const LAS f32x4*)(Wst + r * 32 + 4 * d4); z += w * glr[r]; }
; #pragma unroll
;         for (int e = 0; e < 4; ++e) bc[4 * d4 + e] = (fminf(z[e], 0.f) - __logf(1.f + __expf(-fabsf(z[e])))) * (1.f / 16.f); }
	v_pk_fma_f32 v[96:97], v[64:65], v[96:97], v[100:101] op_sel_hi:[0,1,1]
	v_mul_f32_e64 v93, |v96|, s97
	v_exp_f32_e32 v93, v93
	v_min_f32_e32 v91, 0, v96
	v_pk_fma_f32 v[104:105], v[64:65], v[98:99], v[104:105] op_sel_hi:[0,1,1]
	v_add_f32_e32 v93, 1.0, v93
	v_cmp_gt_f32_e32 vcc, s45, v93
	s_nop 1
	v_cndmask_b32_e64 v95, 0, 32, vcc
	v_ldexp_f32 v93, v93, v95
	v_log_f32_e32 v93, v93
	s_nop 0
	v_mul_f32_e32 v95, 0x3f317217, v93
	v_fma_f32 v95, v93, s31, -v95
	v_fmac_f32_e32 v95, 0x3377d1cf, v93
	v_fmac_f32_e32 v95, 0x3f317217, v93
	v_cmp_lt_f32_e64 s[18:19], |v93|, s44
	s_nop 1
	v_cndmask_b32_e64 v93, v93, v95, s[18:19]
	v_cndmask_b32_e32 v95, 0, v240, vcc
	v_sub_f32_e32 v93, v93, v95
	v_sub_f32_e32 v101, v91, v93
	v_mul_f32_e64 v93, |v97|, s97
	v_exp_f32_e32 v93, v93
	v_min_f32_e32 v91, 0, v97
	v_mul_f32_e32 v102, 0x3d800000, v101
	v_add_f32_e32 v93, 1.0, v93
	v_cmp_gt_f32_e32 vcc, s45, v93
	s_nop 1
	v_cndmask_b32_e64 v95, 0, 32, vcc
	v_ldexp_f32 v93, v93, v95
	v_log_f32_e32 v93, v93
	s_nop 0
	v_mul_f32_e32 v95, 0x3f317217, v93
	v_fma_f32 v95, v93, s31, -v95
	v_fmac_f32_e32 v95, 0x3377d1cf, v93
	v_fmac_f32_e32 v95, 0x3f317217, v93
	v_cmp_lt_f32_e64 s[18:19], |v93|, s44
	s_nop 1
	v_cndmask_b32_e64 v93, v93, v95, s[18:19]
	v_cndmask_b32_e32 v95, 0, v240, vcc
	v_sub_f32_e32 v93, v93, v95
	v_sub_f32_e32 v99, v91, v93
	v_mul_f32_e64 v93, |v104|, s97
	v_exp_f32_e32 v93, v93
	v_min_f32_e32 v91, 0, v104
	v_mul_f32_e32 v100, 0x3d800000, v99
	v_add_f32_e32 v93, 1.0, v93
	v_cmp_gt_f32_e32 vcc, s45, v93
	s_nop 1
	v_cndmask_b32_e64 v95, 0, 32, vcc
	v_ldexp_f32 v93, v93, v95
	v_log_f32_e32 v93, v93
	s_nop 0
	v_mul_f32_e32 v95, 0x3f317217, v93
	v_fma_f32 v95, v93, s31, -v95
	v_fmac_f32_e32 v95, 0x3377d1cf, v93
	v_fmac_f32_e32 v95, 0x3f317217, v93
	v_cmp_lt_f32_e64 s[18:19], |v93|, s44
	s_nop 1
	v_cndmask_b32_e64 v93, v93, v95, s[18:19]
	v_cndmask_b32_e32 v95, 0, v240, vcc
	v_sub_f32_e32 v93, v93, v95
	v_sub_f32_e32 v95, v91, v93
	v_mul_f32_e64 v93, |v105|, s97
	v_exp_f32_e32 v93, v93
	v_min_f32_e32 v91, 0, v105
	ds_read_b128 v[104:107], v103 offset:6416
	v_mul_f32_e32 v98, 0x3d800000, v95
	v_add_f32_e32 v93, 1.0, v93
	v_cmp_gt_f32_e32 vcc, s45, v93
	s_nop 1
	v_cndmask_b32_e64 v96, 0, 32, vcc
	v_ldexp_f32 v93, v93, v96
	v_log_f32_e32 v93, v93
	s_nop 0
	v_mul_f32_e32 v96, 0x3f317217, v93
	v_fma_f32 v96, v93, s31, -v96
	v_fmac_f32_e32 v96, 0x3377d1cf, v93
	v_fmac_f32_e32 v96, 0x3f317217, v93
	v_cmp_lt_f32_e64 s[18:19], |v93|, s44
	s_nop 1
	v_cndmask_b32_e64 v93, v93, v96, s[18:19]
	v_cndmask_b32_e32 v96, 0, v240, vcc
	v_sub_f32_e32 v93, v93, v96
	s_waitcnt lgkmcnt(0)
	v_pk_fma_f32 v[96:97], v[94:95], v[58:59], v[104:105] op_sel_hi:[0,1,1]
	v_pk_fma_f32 v[104:105], v[94:95], v[60:61], v[106:107] op_sel_hi:[0,1,1]
	ds_read_b128 v[58:61], v103 offset:4496
	v_sub_f32_e32 v91, v91, v93
	v_mul_f32_e32 v93, 0x3d800000, v91
	s_waitcnt lgkmcnt(0)
	v_pk_fma_f32 v[104:105], v[92:93], v[60:61], v[104:105] op_sel_hi:[0,1,1]
	v_pk_fma_f32 v[96:97], v[92:93], v[58:59], v[96:97] op_sel_hi:[0,1,1]
	ds_read_b128 v[58:61], v103 offset:4624
	ds_read_b128 v[168:171], v103 offset:4752
	ds_read_b128 v[172:175], v103 offset:4880
	s_waitcnt lgkmcnt(2)
	v_pk_fma_f32 v[96:97], v[90:91], v[58:59], v[96:97] op_sel_hi:[0,1,1]
	v_pk_fma_f32 v[104:105], v[90:91], v[60:61], v[104:105] op_sel_hi:[0,1,1]
	ds_read_b128 v[58:61], v103 offset:5008
	s_waitcnt lgkmcnt(2)
	v_pk_fma_f32 v[104:105], v[88:89], v[170:171], v[104:105] op_sel_hi:[0,1,1]
	v_pk_fma_f32 v[96:97], v[88:89], v[168:169], v[96:97] op_sel_hi:[0,1,1]
	ds_read_b128 v[168:171], v103 offset:5136
	s_waitcnt lgkmcnt(2)
	v_pk_fma_f32 v[96:97], v[86:87], v[172:173], v[96:97] op_sel_hi:[0,1,1]
	v_pk_fma_f32 v[104:105], v[86:87], v[174:175], v[104:105] op_sel_hi:[0,1,1]
	ds_read_b128 v[172:175], v103 offset:5264
	s_waitcnt lgkmcnt(2)
	v_pk_fma_f32 v[104:105], v[84:85], v[60:61], v[104:105] op_sel_hi:[0,1,1]
	v_pk_fma_f32 v[96:97], v[84:85], v[58:59], v[96:97] op_sel_hi:[0,1,1]
	ds_read_b128 v[58:61], v103 offset:5392
	s_waitcnt lgkmcnt(2)
	v_pk_fma_f32 v[96:97], v[82:83], v[168:169], v[96:97] op_sel_hi:[0,1,1]
	v_pk_fma_f32 v[104:105], v[82:83], v[170:171], v[104:105] op_sel_hi:[0,1,1]
	ds_read_b128 v[168:171], v103 offset:5520
	s_waitcnt lgkmcnt(2)
	v_pk_fma_f32 v[104:105], v[80:81], v[174:175], v[104:105] op_sel_hi:[0,1,1]
	v_pk_fma_f32 v[96:97], v[80:81], v[172:173], v[96:97] op_sel_hi:[0,1,1]
	ds_read_b128 v[172:175], v103 offset:5648
	s_waitcnt lgkmcnt(2)
	v_pk_fma_f32 v[96:97], v[78:79], v[58:59], v[96:97] op_sel_hi:[0,1,1]
	v_pk_fma_f32 v[104:105], v[78:79], v[60:61], v[104:105] op_sel_hi:[0,1,1]
	ds_read_b128 v[58:61], v103 offset:5776
	s_waitcnt lgkmcnt(2)
	v_pk_fma_f32 v[104:105], v[76:77], v[170:171], v[104:105] op_sel_hi:[0,1,1]
	v_pk_fma_f32 v[96:97], v[76:77], v[168:169], v[96:97] op_sel_hi:[0,1,1]
	ds_read_b128 v[168:171], v103 offset:5904
	s_waitcnt lgkmcnt(2)
	v_pk_fma_f32 v[96:97], v[74:75], v[172:173], v[96:97] op_sel_hi:[0,1,1]
	v_pk_fma_f32 v[104:105], v[74:75], v[174:175], v[104:105] op_sel_hi:[0,1,1]
	ds_read_b128 v[172:175], v103 offset:6032
	s_waitcnt lgkmcnt(2)
	v_pk_fma_f32 v[104:105], v[72:73], v[60:61], v[104:105] op_sel_hi:[0,1,1]
	v_pk_fma_f32 v[96:97], v[72:73], v[58:59], v[96:97] op_sel_hi:[0,1,1]
	ds_read_b128 v[58:61], v103 offset:6160
	s_waitcnt lgkmcnt(2)
	v_pk_fma_f32 v[96:97], v[70:71], v[168:169], v[96:97] op_sel_hi:[0,1,1]
	v_pk_fma_f32 v[104:105], v[70:71], v[170:171], v[104:105] op_sel_hi:[0,1,1]
	s_waitcnt lgkmcnt(1)
	v_pk_fma_f32 v[104:105], v[68:69], v[174:175], v[104:105] op_sel_hi:[0,1,1]
	v_pk_fma_f32 v[96:97], v[68:69], v[172:173], v[96:97] op_sel_hi:[0,1,1]
	s_waitcnt lgkmcnt(0)
; #define LAS __attribute__((address_space(3)))
; __device__ __forceinline__ void gla_gates(const bf16* prow, const float* wg, const float* bg, int h, int lane, float (&bc)[32], LAS float* Wst) {
;     ...
;     for (int d4 = 0; d4 < 8; ++d4) { f32x4 z = *(const LAS f32x4*)(Wst + 512 + 4 * d4);
; #pragma unroll
;         for (int r = 0; r < 16; ++r) { const f32x4 w = *(const LAS f32x4*)(Wst + r * 32 + 4 * d4); z += w * glr[r]; }
; #pragma unroll
;         for (int e = 0; e < 4; ++e) bc[4 * d4 + e] = (fminf(z[e], 0.f) - __logf(1.f + __expf(-fabsf(z[e])))) * (1.f / 16.f); }
	v_pk_fma_f32 v[96:97], v[66:67], v[58:59], v[96:97] op_sel_hi:[0,1,1]
	v_pk_fma_f32 v[104:105], v[66:67], v[60:61], v[104:105] op_sel_hi:[0,1,1]
	ds_read_b128 v[58:61], v103 offset:6288
	s_waitcnt lgkmcnt(0)
	v_pk_fma_f32 v[58:59], v[64:65], v[58:59], v[96:97] op_sel_hi:[0,1,1]
	v_min_f32_e32 v96, 0, v58
	v_mul_f32_e64 v58, |v58|, s97
	v_exp_f32_e32 v58, v58
	v_pk_fma_f32 v[60:61], v[64:65], v[60:61], v[104:105] op_sel_hi:[0,1,1]
	v_add_f32_e32 v58, 1.0, v58
	v_cmp_gt_f32_e32 vcc, s45, v58
	s_nop 1
	v_cndmask_b32_e64 v97, 0, 32, vcc
	v_ldexp_f32 v58, v58, v97
	v_log_f32_e32 v58, v58
	s_nop 0
	v_mul_f32_e32 v97, 0x3f317217, v58
	v_fma_f32 v97, v58, s31, -v97
	v_fmac_f32_e32 v97, 0x3377d1cf, v58
	v_fmac_f32_e32 v97, 0x3f317217, v58
	v_cmp_lt_f32_e64 s[18:19], |v58|, s44
	s_nop 1
	v_cndmask_b32_e64 v58, v58, v97, s[18:19]
	v_cndmask_b32_e32 v97, 0, v240, vcc
	v_sub_f32_e32 v58, v58, v97
	v_sub_f32_e32 v110, v96, v58
	v_min_f32_e32 v58, 0, v59
	v_mul_f32_e64 v59, |v59|, s97
	v_exp_f32_e32 v59, v59
	v_mul_f32_e32 v111, 0x3d800000, v110
	v_add_f32_e32 v59, 1.0, v59
	v_cmp_gt_f32_e32 vcc, s45, v59
	s_nop 1
	v_cndmask_b32_e64 v96, 0, 32, vcc
	v_ldexp_f32 v59, v59, v96
	v_log_f32_e32 v59, v59
	s_nop 0
	v_mul_f32_e32 v96, 0x3f317217, v59
	v_fma_f32 v96, v59, s31, -v96
	v_fmac_f32_e32 v96, 0x3377d1cf, v59
	v_fmac_f32_e32 v96, 0x3f317217, v59
	v_cmp_lt_f32_e64 s[18:19], |v59|, s44
	s_nop 1
	v_cndmask_b32_e64 v59, v59, v96, s[18:19]
	v_cndmask_b32_e32 v96, 0, v240, vcc
	v_sub_f32_e32 v59, v59, v96
	v_sub_f32_e32 v108, v58, v59
	v_mul_f32_e64 v59, |v60|, s97
	v_exp_f32_e32 v59, v59
	v_min_f32_e32 v58, 0, v60
	v_mul_f32_e32 v109, 0x3d800000, v108
	v_add_f32_e32 v59, 1.0, v59
	v_cmp_gt_f32_e32 vcc, s45, v59
	s_nop 1
	v_cndmask_b32_e64 v60, 0, 32, vcc
	v_ldexp_f32 v59, v59, v60
	v_log_f32_e32 v59, v59
	s_nop 0
	v_mul_f32_e32 v60, 0x3f317217, v59
	v_fma_f32 v60, v59, s31, -v60
	v_fmac_f32_e32 v60, 0x3377d1cf, v59
	v_fmac_f32_e32 v60, 0x3f317217, v59
	v_cmp_lt_f32_e64 s[18:19], |v59|, s44
	s_nop 1
	v_cndmask_b32_e64 v59, v59, v60, s[18:19]
	v_cndmask_b32_e32 v60, 0, v240, vcc
	v_sub_f32_e32 v59, v59, v60
	v_sub_f32_e32 v106, v58, v59
	v_mul_f32_e64 v59, |v61|, s97
	v_exp_f32_e32 v59, v59
	v_min_f32_e32 v58, 0, v61
	v_mul_f32_e32 v107, 0x3d800000, v106
	v_add_f32_e32 v59, 1.0, v59
	v_cmp_gt_f32_e32 vcc, s45, v59
	s_nop 1
	v_cndmask_b32_e64 v60, 0, 32, vcc
	v_ldexp_f32 v59, v59, v60
	v_log_f32_e32 v59, v59
	s_nop 0
	v_mul_f32_e32 v60, 0x3f317217, v59
	v_fma_f32 v60, v59, s31, -v60
	v_fmac_f32_e32 v60, 0x3377d1cf, v59
	v_fmac_f32_e32 v60, 0x3f317217, v59
	v_cmp_lt_f32_e64 s[18:19], |v59|, s44
	s_nop 1
	v_cndmask_b32_e64 v59, v59, v60, s[18:19]
	v_cndmask_b32_e32 v60, 0, v240, vcc
	v_sub_f32_e32 v59, v59, v60
	v_sub_f32_e32 v104, v58, v59
	ds_read_b128 v[58:61], v103 offset:6432
	v_mul_f32_e32 v105, 0x3d800000, v104
	s_waitcnt lgkmcnt(0)
	v_pk_fma_f32 v[58:59], v[94:95], v[54:55], v[58:59] op_sel_hi:[0,1,1]
	v_pk_fma_f32 v[60:61], v[94:95], v[56:57], v[60:61] op_sel_hi:[0,1,1]
	ds_read_b128 v[54:57], v103 offset:4512
	ds_read_b128 v[168:171], v103 offset:4640
	ds_read_b128 v[172:175], v103 offset:4768
	s_waitcnt lgkmcnt(2)
	v_pk_fma_f32 v[60:61], v[92:93], v[56:57], v[60:61] op_sel_hi:[0,1,1]
	v_pk_fma_f32 v[58:59], v[92:93], v[54:55], v[58:59] op_sel_hi:[0,1,1]
	ds_read_b128 v[54:57], v103 offset:4896
	s_waitcnt lgkmcnt(2)
	v_pk_fma_f32 v[58:59], v[90:91], v[168:169], v[58:59] op_sel_hi:[0,1,1]
	v_pk_fma_f32 v[60:61], v[90:91], v[170:171], v[60:61] op_sel_hi:[0,1,1]
	ds_read_b128 v[168:171], v103 offset:5024
	s_waitcnt lgkmcnt(2)
	v_pk_fma_f32 v[60:61], v[88:89], v[174:175], v[60:61] op_sel_hi:[0,1,1]
	v_pk_fma_f32 v[58:59], v[88:89], v[172:173], v[58:59] op_sel_hi:[0,1,1]
	ds_read_b128 v[172:175], v103 offset:5152
	s_waitcnt lgkmcnt(2)
	v_pk_fma_f32 v[58:59], v[86:87], v[54:55], v[58:59] op_sel_hi:[0,1,1]
	v_pk_fma_f32 v[60:61], v[86:87], v[56:57], v[60:61] op_sel_hi:[0,1,1]
	ds_read_b128 v[54:57], v103 offset:5280
	s_waitcnt lgkmcnt(2)
	v_pk_fma_f32 v[60:61], v[84:85], v[170:171], v[60:61] op_sel_hi:[0,1,1]
	v_pk_fma_f32 v[58:59], v[84:85], v[168:169], v[58:59] op_sel_hi:[0,1,1]
	ds_read_b128 v[168:171], v103 offset:5408
	s_waitcnt lgkmcnt(2)
	v_pk_fma_f32 v[58:59], v[82:83], v[172:173], v[58:59] op_sel_hi:[0,1,1]
	v_pk_fma_f32 v[60:61], v[82:83], v[174:175], v[60:61] op_sel_hi:[0,1,1]
	ds_read_b128 v[172:175], v103 offset:5536
	s_waitcnt lgkmcnt(2)
	v_pk_fma_f32 v[60:61], v[80:81], v[56:57], v[60:61] op_sel_hi:[0,1,1]
	v_pk_fma_f32 v[58:59], v[80:81], v[54:55], v[58:59] op_sel_hi:[0,1,1]
	ds_read_b128 v[54:57], v103 offset:5664
	s_waitcnt lgkmcnt(2)
	v_pk_fma_f32 v[58:59], v[78:79], v[168:169], v[58:59] op_sel_hi:[0,1,1]
	v_pk_fma_f32 v[60:61], v[78:79], v[170:171], v[60:61] op_sel_hi:[0,1,1]
	ds_read_b128 v[168:171], v103 offset:5792
	s_waitcnt lgkmcnt(2)
	v_pk_fma_f32 v[60:61], v[76:77], v[174:175], v[60:61] op_sel_hi:[0,1,1]
	v_pk_fma_f32 v[58:59], v[76:77], v[172:173], v[58:59] op_sel_hi:[0,1,1]
	ds_read_b128 v[172:175], v103 offset:5920
	s_waitcnt lgkmcnt(2)
	v_pk_fma_f32 v[58:59], v[74:75], v[54:55], v[58:59] op_sel_hi:[0,1,1]
	v_pk_fma_f32 v[60:61], v[74:75], v[56:57], v[60:61] op_sel_hi:[0,1,1]
	ds_read_b128 v[54:57], v103 offset:6048
	s_waitcnt lgkmcnt(2)
	v_pk_fma_f32 v[60:61], v[72:73], v[170:171], v[60:61] op_sel_hi:[0,1,1]
	v_pk_fma_f32 v[58:59], v[72:73], v[168:169], v[58:59] op_sel_hi:[0,1,1]
	ds_read_b128 v[168:171], v103 offset:6176
	s_waitcnt lgkmcnt(2)
	v_pk_fma_f32 v[58:59], v[70:71], v[172:173], v[58:59] op_sel_hi:[0,1,1]
	v_pk_fma_f32 v[60:61], v[70:71], v[174:175], v[60:61] op_sel_hi:[0,1,1]
	s_waitcnt lgkmcnt(1)
; #define LAS __attribute__((address_space(3)))
; __device__ __forceinline__ void gla_gates(const bf16* prow, const float* wg, const float* bg, int h, int lane, float (&bc)[32], LAS float* Wst) {
;     ...
;     for (int d4 = 0; d4 < 8; ++d4) { f32x4 z = *(const LAS f32x4*)(Wst + 512 + 4 * d4);
; #pragma unroll
;         for (int r = 0; r < 16; ++r) { const f32x4 w = *(const LAS f32x4*)(Wst + r * 32 + 4 * d4); z += w * glr[r]; }
; #pragma unroll
;         for (int e = 0; e < 4; ++e) bc[4 * d4 + e] = (fminf(z[e], 0.f) - __logf(1.f + __expf(-fabsf(z[e])))) * (1.f / 16.f); }
	v_pk_fma_f32 v[60:61], v[68:69], v[56:57], v[60:61] op_sel_hi:[0,1,1]
	v_pk_fma_f32 v[58:59], v[68:69], v[54:55], v[58:59] op_sel_hi:[0,1,1]
	s_waitcnt lgkmcnt(0)
	v_pk_fma_f32 v[58:59], v[66:67], v[168:169], v[58:59] op_sel_hi:[0,1,1]
	v_pk_fma_f32 v[60:61], v[66:67], v[170:171], v[60:61] op_sel_hi:[0,1,1]
	ds_read_b128 v[54:57], v103 offset:6304
	s_waitcnt lgkmcnt(0)
	v_pk_fma_f32 v[54:55], v[64:65], v[54:55], v[58:59] op_sel_hi:[0,1,1]
	v_min_f32_e32 v58, 0, v54
	v_mul_f32_e64 v54, |v54|, s97
	v_exp_f32_e32 v54, v54
	v_pk_fma_f32 v[56:57], v[64:65], v[56:57], v[60:61] op_sel_hi:[0,1,1]
	v_add_f32_e32 v54, 1.0, v54
	v_cmp_gt_f32_e32 vcc, s45, v54
	s_nop 1
	v_cndmask_b32_e64 v59, 0, 32, vcc
	v_ldexp_f32 v54, v54, v59
	v_log_f32_e32 v54, v54
	s_nop 0
	v_mul_f32_e32 v59, 0x3f317217, v54
	v_fma_f32 v59, v54, s31, -v59
	v_fmac_f32_e32 v59, 0x3377d1cf, v54
	v_fmac_f32_e32 v59, 0x3f317217, v54
	v_cmp_lt_f32_e64 s[18:19], |v54|, s44
	s_nop 1
	v_cndmask_b32_e64 v54, v54, v59, s[18:19]
	v_cndmask_b32_e32 v59, 0, v240, vcc
	v_sub_f32_e32 v54, v54, v59
	v_sub_f32_e32 v96, v58, v54
	v_min_f32_e32 v54, 0, v55
	v_mul_f32_e64 v55, |v55|, s97
	v_exp_f32_e32 v55, v55
	v_mul_f32_e32 v97, 0x3d800000, v96
	v_add_f32_e32 v55, 1.0, v55
	v_cmp_gt_f32_e32 vcc, s45, v55
	s_nop 1
	v_cndmask_b32_e64 v58, 0, 32, vcc
	v_ldexp_f32 v55, v55, v58
	v_log_f32_e32 v55, v55
	s_nop 0
	v_mul_f32_e32 v58, 0x3f317217, v55
	v_fma_f32 v58, v55, s31, -v58
	v_fmac_f32_e32 v58, 0x3377d1cf, v55
	v_fmac_f32_e32 v58, 0x3f317217, v55
	v_cmp_lt_f32_e64 s[18:19], |v55|, s44
	s_nop 1
	v_cndmask_b32_e64 v55, v55, v58, s[18:19]
	v_cndmask_b32_e32 v58, 0, v240, vcc
	v_sub_f32_e32 v55, v55, v58
	v_sub_f32_e32 v60, v54, v55
	v_mul_f32_e64 v55, |v56|, s97
	v_exp_f32_e32 v55, v55
	v_min_f32_e32 v54, 0, v56
	v_mul_f32_e32 v61, 0x3d800000, v60
	v_add_f32_e32 v55, 1.0, v55
	v_cmp_gt_f32_e32 vcc, s45, v55
	s_nop 1
	v_cndmask_b32_e64 v56, 0, 32, vcc
	v_ldexp_f32 v55, v55, v56
	v_log_f32_e32 v55, v55
	s_nop 0
	v_mul_f32_e32 v56, 0x3f317217, v55
	v_fma_f32 v56, v55, s31, -v56
	v_fmac_f32_e32 v56, 0x3377d1cf, v55
	v_fmac_f32_e32 v56, 0x3f317217, v55
	v_cmp_lt_f32_e64 s[18:19], |v55|, s44
	s_nop 1
	v_cndmask_b32_e64 v55, v55, v56, s[18:19]
	v_cndmask_b32_e32 v56, 0, v240, vcc
	v_sub_f32_e32 v55, v55, v56
	v_sub_f32_e32 v58, v54, v55
	v_mul_f32_e64 v55, |v57|, s97
	v_exp_f32_e32 v55, v55
	v_min_f32_e32 v54, 0, v57
	v_mul_f32_e32 v59, 0x3d800000, v58
	v_add_f32_e32 v55, 1.0, v55
	v_cmp_gt_f32_e32 vcc, s45, v55
	s_nop 1
	v_cndmask_b32_e64 v56, 0, 32, vcc
	v_ldexp_f32 v55, v55, v56
	v_log_f32_e32 v55, v55
	s_nop 0
	v_mul_f32_e32 v56, 0x3f317217, v55
	v_fma_f32 v56, v55, s31, -v56
	v_fmac_f32_e32 v56, 0x3377d1cf, v55
	v_fmac_f32_e32 v56, 0x3f317217, v55
	v_cmp_lt_f32_e64 s[18:19], |v55|, s44
	s_nop 1
	v_cndmask_b32_e64 v55, v55, v56, s[18:19]
	v_cndmask_b32_e32 v56, 0, v240, vcc
	v_sub_f32_e32 v55, v55, v56
	v_sub_f32_e32 v56, v54, v55
	v_pk_fma_f32 v[54:55], v[94:95], v[50:51], v[112:113] op_sel_hi:[0,1,1]
	v_pk_fma_f32 v[112:113], v[94:95], v[52:53], v[114:115] op_sel_hi:[0,1,1]
	ds_read_b128 v[50:53], v103 offset:4528
	v_mul_f32_e32 v57, 0x3d800000, v56
	s_waitcnt lgkmcnt(0)
	v_pk_fma_f32 v[112:113], v[92:93], v[52:53], v[112:113] op_sel_hi:[0,1,1]
	v_pk_fma_f32 v[54:55], v[92:93], v[50:51], v[54:55] op_sel_hi:[0,1,1]
	ds_read_b128 v[50:53], v103 offset:4656
	ds_read_b128 v[168:171], v103 offset:4784
	ds_read_b128 v[172:175], v103 offset:4912
	s_waitcnt lgkmcnt(2)
	v_pk_fma_f32 v[54:55], v[90:91], v[50:51], v[54:55] op_sel_hi:[0,1,1]
	v_pk_fma_f32 v[112:113], v[90:91], v[52:53], v[112:113] op_sel_hi:[0,1,1]
	ds_read_b128 v[50:53], v103 offset:5040
	s_waitcnt lgkmcnt(2)
	v_pk_fma_f32 v[112:113], v[88:89], v[170:171], v[112:113] op_sel_hi:[0,1,1]
	v_pk_fma_f32 v[54:55], v[88:89], v[168:169], v[54:55] op_sel_hi:[0,1,1]
	ds_read_b128 v[168:171], v103 offset:5168
	s_waitcnt lgkmcnt(2)
	v_pk_fma_f32 v[54:55], v[86:87], v[172:173], v[54:55] op_sel_hi:[0,1,1]
	v_pk_fma_f32 v[112:113], v[86:87], v[174:175], v[112:113] op_sel_hi:[0,1,1]
	ds_read_b128 v[172:175], v103 offset:5296
	s_waitcnt lgkmcnt(2)
	v_pk_fma_f32 v[112:113], v[84:85], v[52:53], v[112:113] op_sel_hi:[0,1,1]
	v_pk_fma_f32 v[54:55], v[84:85], v[50:51], v[54:55] op_sel_hi:[0,1,1]
	ds_read_b128 v[50:53], v103 offset:5424
	s_waitcnt lgkmcnt(2)
	v_pk_fma_f32 v[54:55], v[82:83], v[168:169], v[54:55] op_sel_hi:[0,1,1]
	v_pk_fma_f32 v[112:113], v[82:83], v[170:171], v[112:113] op_sel_hi:[0,1,1]
	ds_read_b128 v[168:171], v103 offset:5552
	s_waitcnt lgkmcnt(2)
	v_pk_fma_f32 v[112:113], v[80:81], v[174:175], v[112:113] op_sel_hi:[0,1,1]
	v_pk_fma_f32 v[54:55], v[80:81], v[172:173], v[54:55] op_sel_hi:[0,1,1]
	ds_read_b128 v[172:175], v103 offset:5680
	s_waitcnt lgkmcnt(2)
	v_pk_fma_f32 v[54:55], v[78:79], v[50:51], v[54:55] op_sel_hi:[0,1,1]
	v_pk_fma_f32 v[112:113], v[78:79], v[52:53], v[112:113] op_sel_hi:[0,1,1]
	ds_read_b128 v[50:53], v103 offset:5808
	s_waitcnt lgkmcnt(2)
	v_pk_fma_f32 v[112:113], v[76:77], v[170:171], v[112:113] op_sel_hi:[0,1,1]
	v_pk_fma_f32 v[54:55], v[76:77], v[168:169], v[54:55] op_sel_hi:[0,1,1]
	ds_read_b128 v[168:171], v103 offset:5936
	s_waitcnt lgkmcnt(2)
	v_pk_fma_f32 v[54:55], v[74:75], v[172:173], v[54:55] op_sel_hi:[0,1,1]
	v_pk_fma_f32 v[112:113], v[74:75], v[174:175], v[112:113] op_sel_hi:[0,1,1]
	ds_read_b128 v[172:175], v103 offset:6064
	s_waitcnt lgkmcnt(2)
	v_pk_fma_f32 v[112:113], v[72:73], v[52:53], v[112:113] op_sel_hi:[0,1,1]
	v_pk_fma_f32 v[54:55], v[72:73], v[50:51], v[54:55] op_sel_hi:[0,1,1]
	ds_read_b128 v[50:53], v103 offset:6192
	s_waitcnt lgkmcnt(2)
; #define LAS __attribute__((address_space(3)))
; __device__ __forceinline__ void gla_gates(const bf16* prow, const float* wg, const float* bg, int h, int lane, float (&bc)[32], LAS float* Wst) {
;     ...
;     for (int d4 = 0; d4 < 8; ++d4) { f32x4 z = *(const LAS f32x4*)(Wst + 512 + 4 * d4);
; #pragma unroll
;         for (int r = 0; r < 16; ++r) { const f32x4 w = *(const LAS f32x4*)(Wst + r * 32 + 4 * d4); z += w * glr[r]; }
; #pragma unroll
;         for (int e = 0; e < 4; ++e) bc[4 * d4 + e] = (fminf(z[e], 0.f) - __logf(1.f + __expf(-fabsf(z[e])))) * (1.f / 16.f); }
	v_pk_fma_f32 v[54:55], v[70:71], v[168:169], v[54:55] op_sel_hi:[0,1,1]
	v_pk_fma_f32 v[112:113], v[70:71], v[170:171], v[112:113] op_sel_hi:[0,1,1]
	s_waitcnt lgkmcnt(1)
	v_pk_fma_f32 v[112:113], v[68:69], v[174:175], v[112:113] op_sel_hi:[0,1,1]
	v_pk_fma_f32 v[54:55], v[68:69], v[172:173], v[54:55] op_sel_hi:[0,1,1]
	s_waitcnt lgkmcnt(0)
	v_pk_fma_f32 v[54:55], v[66:67], v[50:51], v[54:55] op_sel_hi:[0,1,1]
	v_pk_fma_f32 v[112:113], v[66:67], v[52:53], v[112:113] op_sel_hi:[0,1,1]
	ds_read_b128 v[50:53], v103 offset:6320
	s_waitcnt lgkmcnt(0)
	v_pk_fma_f32 v[50:51], v[64:65], v[50:51], v[54:55] op_sel_hi:[0,1,1]
	v_min_f32_e32 v54, 0, v50
	v_mul_f32_e64 v50, |v50|, s97
	v_exp_f32_e32 v50, v50
	v_pk_fma_f32 v[52:53], v[64:65], v[52:53], v[112:113] op_sel_hi:[0,1,1]
	v_add_f32_e32 v50, 1.0, v50
	v_cmp_gt_f32_e32 vcc, s45, v50
	s_nop 1
	v_cndmask_b32_e64 v55, 0, 32, vcc
	v_ldexp_f32 v50, v50, v55
	v_log_f32_e32 v50, v50
	s_nop 0
	v_mul_f32_e32 v55, 0x3f317217, v50
	v_fma_f32 v55, v50, s31, -v55
	v_fmac_f32_e32 v55, 0x3377d1cf, v50
	v_fmac_f32_e32 v55, 0x3f317217, v50
	v_cmp_lt_f32_e64 s[18:19], |v50|, s44
	s_nop 1
	v_cndmask_b32_e64 v50, v50, v55, s[18:19]
	v_cndmask_b32_e32 v55, 0, v240, vcc
	v_sub_f32_e32 v50, v50, v55
	v_sub_f32_e32 v126, v54, v50
	v_min_f32_e32 v50, 0, v51
	v_mul_f32_e64 v51, |v51|, s97
	v_exp_f32_e32 v51, v51
	v_mul_f32_e32 v127, 0x3d800000, v126
	v_add_f32_e32 v51, 1.0, v51
	v_cmp_gt_f32_e32 vcc, s45, v51
	s_nop 1
	v_cndmask_b32_e64 v54, 0, 32, vcc
	v_ldexp_f32 v51, v51, v54
	v_log_f32_e32 v51, v51
	s_nop 0
	v_mul_f32_e32 v54, 0x3f317217, v51
	v_fma_f32 v54, v51, s31, -v54
	v_fmac_f32_e32 v54, 0x3377d1cf, v51
	v_fmac_f32_e32 v54, 0x3f317217, v51
	v_cmp_lt_f32_e64 s[18:19], |v51|, s44
	s_nop 1
	v_cndmask_b32_e64 v51, v51, v54, s[18:19]
	v_cndmask_b32_e32 v54, 0, v240, vcc
	v_sub_f32_e32 v51, v51, v54
	v_sub_f32_e32 v124, v50, v51
	v_mul_f32_e64 v51, |v52|, s97
	v_exp_f32_e32 v51, v51
	v_min_f32_e32 v50, 0, v52
	v_mul_f32_e32 v125, 0x3d800000, v124
	v_add_f32_e32 v51, 1.0, v51
	v_cmp_gt_f32_e32 vcc, s45, v51
	s_nop 1
	v_cndmask_b32_e64 v52, 0, 32, vcc
	v_ldexp_f32 v51, v51, v52
	v_log_f32_e32 v51, v51
	s_nop 0
	v_mul_f32_e32 v52, 0x3f317217, v51
	v_fma_f32 v52, v51, s31, -v52
	v_fmac_f32_e32 v52, 0x3377d1cf, v51
	v_fmac_f32_e32 v52, 0x3f317217, v51
	v_cmp_lt_f32_e64 s[18:19], |v51|, s44
	s_nop 1
	v_cndmask_b32_e64 v51, v51, v52, s[18:19]
	v_cndmask_b32_e32 v52, 0, v240, vcc
	v_sub_f32_e32 v51, v51, v52
	v_sub_f32_e32 v122, v50, v51
	v_mul_f32_e64 v51, |v53|, s97
	v_exp_f32_e32 v51, v51
	v_min_f32_e32 v50, 0, v53
	v_mul_f32_e32 v123, 0x3d800000, v122
	v_add_f32_e32 v51, 1.0, v51
	v_cmp_gt_f32_e32 vcc, s45, v51
	s_nop 1
	v_cndmask_b32_e64 v52, 0, 32, vcc
	v_ldexp_f32 v51, v51, v52
	v_log_f32_e32 v51, v51
	s_nop 0
	v_mul_f32_e32 v52, 0x3f317217, v51
	v_fma_f32 v52, v51, s31, -v52
	v_fmac_f32_e32 v52, 0x3377d1cf, v51
	v_fmac_f32_e32 v52, 0x3f317217, v51
	v_cmp_lt_f32_e64 s[18:19], |v51|, s44
	s_nop 1
	v_cndmask_b32_e64 v51, v51, v52, s[18:19]
	v_cndmask_b32_e32 v52, 0, v240, vcc
	v_sub_f32_e32 v51, v51, v52
	v_sub_f32_e32 v120, v50, v51
	ds_read_b128 v[50:53], v103 offset:6464
	ds_read_b128 v[112:115], v103 offset:4416
	v_mul_f32_e32 v121, 0x3d800000, v120
	s_waitcnt lgkmcnt(0)
	v_pk_fma_f32 v[54:55], v[94:95], v[112:113], v[50:51] op_sel_hi:[0,1,1]
	v_pk_fma_f32 v[112:113], v[94:95], v[114:115], v[52:53] op_sel_hi:[0,1,1]
	ds_read_b128 v[50:53], v103 offset:4544
	ds_read_b128 v[168:171], v103 offset:4672
	ds_read_b128 v[172:175], v103 offset:4800
	s_waitcnt lgkmcnt(2)
	v_pk_fma_f32 v[112:113], v[92:93], v[52:53], v[112:113] op_sel_hi:[0,1,1]
	v_pk_fma_f32 v[54:55], v[92:93], v[50:51], v[54:55] op_sel_hi:[0,1,1]
	ds_read_b128 v[50:53], v103 offset:4928
	s_waitcnt lgkmcnt(2)
	v_pk_fma_f32 v[54:55], v[90:91], v[168:169], v[54:55] op_sel_hi:[0,1,1]
	v_pk_fma_f32 v[112:113], v[90:91], v[170:171], v[112:113] op_sel_hi:[0,1,1]
	ds_read_b128 v[168:171], v103 offset:5056
	s_waitcnt lgkmcnt(2)
	v_pk_fma_f32 v[112:113], v[88:89], v[174:175], v[112:113] op_sel_hi:[0,1,1]
	v_pk_fma_f32 v[54:55], v[88:89], v[172:173], v[54:55] op_sel_hi:[0,1,1]
	ds_read_b128 v[172:175], v103 offset:5184
	s_waitcnt lgkmcnt(2)
	v_pk_fma_f32 v[54:55], v[86:87], v[50:51], v[54:55] op_sel_hi:[0,1,1]
	v_pk_fma_f32 v[112:113], v[86:87], v[52:53], v[112:113] op_sel_hi:[0,1,1]
	ds_read_b128 v[50:53], v103 offset:5312
	s_waitcnt lgkmcnt(2)
	v_pk_fma_f32 v[112:113], v[84:85], v[170:171], v[112:113] op_sel_hi:[0,1,1]
	v_pk_fma_f32 v[54:55], v[84:85], v[168:169], v[54:55] op_sel_hi:[0,1,1]
	ds_read_b128 v[168:171], v103 offset:5440
	s_waitcnt lgkmcnt(2)
	v_pk_fma_f32 v[54:55], v[82:83], v[172:173], v[54:55] op_sel_hi:[0,1,1]
	v_pk_fma_f32 v[112:113], v[82:83], v[174:175], v[112:113] op_sel_hi:[0,1,1]
	ds_read_b128 v[172:175], v103 offset:5568
	s_waitcnt lgkmcnt(2)
	v_pk_fma_f32 v[112:113], v[80:81], v[52:53], v[112:113] op_sel_hi:[0,1,1]
	v_pk_fma_f32 v[54:55], v[80:81], v[50:51], v[54:55] op_sel_hi:[0,1,1]
	ds_read_b128 v[50:53], v103 offset:5696
	s_waitcnt lgkmcnt(2)
	v_pk_fma_f32 v[54:55], v[78:79], v[168:169], v[54:55] op_sel_hi:[0,1,1]
	v_pk_fma_f32 v[112:113], v[78:79], v[170:171], v[112:113] op_sel_hi:[0,1,1]
	ds_read_b128 v[168:171], v103 offset:5824
	s_waitcnt lgkmcnt(2)
	v_pk_fma_f32 v[112:113], v[76:77], v[174:175], v[112:113] op_sel_hi:[0,1,1]
	v_pk_fma_f32 v[54:55], v[76:77], v[172:173], v[54:55] op_sel_hi:[0,1,1]
	ds_read_b128 v[172:175], v103 offset:5952
	s_waitcnt lgkmcnt(2)
	v_pk_fma_f32 v[54:55], v[74:75], v[50:51], v[54:55] op_sel_hi:[0,1,1]
	v_pk_fma_f32 v[112:113], v[74:75], v[52:53], v[112:113] op_sel_hi:[0,1,1]
	ds_read_b128 v[50:53], v103 offset:6080
	s_waitcnt lgkmcnt(2)
; #define LAS __attribute__((address_space(3)))
; __device__ __forceinline__ void gla_gates(const bf16* prow, const float* wg, const float* bg, int h, int lane, float (&bc)[32], LAS float* Wst) {
;     ...
;     for (int d4 = 0; d4 < 8; ++d4) { f32x4 z = *(const LAS f32x4*)(Wst + 512 + 4 * d4);
; #pragma unroll
;         for (int r = 0; r < 16; ++r) { const f32x4 w = *(const LAS f32x4*)(Wst + r * 32 + 4 * d4); z += w * glr[r]; }
; #pragma unroll
;         for (int e = 0; e < 4; ++e) bc[4 * d4 + e] = (fminf(z[e], 0.f) - __logf(1.f + __expf(-fabsf(z[e])))) * (1.f / 16.f); }
	v_pk_fma_f32 v[112:113], v[72:73], v[170:171], v[112:113] op_sel_hi:[0,1,1]
	v_pk_fma_f32 v[54:55], v[72:73], v[168:169], v[54:55] op_sel_hi:[0,1,1]
	ds_read_b128 v[168:171], v103 offset:6208
	s_waitcnt lgkmcnt(2)
	v_pk_fma_f32 v[54:55], v[70:71], v[172:173], v[54:55] op_sel_hi:[0,1,1]
	v_pk_fma_f32 v[112:113], v[70:71], v[174:175], v[112:113] op_sel_hi:[0,1,1]
	s_waitcnt lgkmcnt(1)
	v_pk_fma_f32 v[112:113], v[68:69], v[52:53], v[112:113] op_sel_hi:[0,1,1]
	v_pk_fma_f32 v[54:55], v[68:69], v[50:51], v[54:55] op_sel_hi:[0,1,1]
	s_waitcnt lgkmcnt(0)
	v_pk_fma_f32 v[54:55], v[66:67], v[168:169], v[54:55] op_sel_hi:[0,1,1]
	v_pk_fma_f32 v[112:113], v[66:67], v[170:171], v[112:113] op_sel_hi:[0,1,1]
	ds_read_b128 v[50:53], v103 offset:6336
	s_waitcnt lgkmcnt(0)
	v_pk_fma_f32 v[50:51], v[64:65], v[50:51], v[54:55] op_sel_hi:[0,1,1]
	v_min_f32_e32 v54, 0, v50
	v_mul_f32_e64 v50, |v50|, s97
	v_exp_f32_e32 v50, v50
	v_pk_fma_f32 v[52:53], v[64:65], v[52:53], v[112:113] op_sel_hi:[0,1,1]
	v_add_f32_e32 v50, 1.0, v50
	v_cmp_gt_f32_e32 vcc, s45, v50
	s_nop 1
	v_cndmask_b32_e64 v55, 0, 32, vcc
	v_ldexp_f32 v50, v50, v55
	v_log_f32_e32 v50, v50
	s_nop 0
	v_mul_f32_e32 v55, 0x3f317217, v50
	v_fma_f32 v55, v50, s31, -v55
	v_fmac_f32_e32 v55, 0x3377d1cf, v50
	v_fmac_f32_e32 v55, 0x3f317217, v50
	v_cmp_lt_f32_e64 s[18:19], |v50|, s44
	s_nop 1
	v_cndmask_b32_e64 v50, v50, v55, s[18:19]
	v_cndmask_b32_e32 v55, 0, v240, vcc
	v_sub_f32_e32 v50, v50, v55
	v_sub_f32_e32 v118, v54, v50
	v_min_f32_e32 v50, 0, v51
	v_mul_f32_e64 v51, |v51|, s97
	v_exp_f32_e32 v51, v51
	v_mul_f32_e32 v119, 0x3d800000, v118
	v_add_f32_e32 v51, 1.0, v51
	v_cmp_gt_f32_e32 vcc, s45, v51
	s_nop 1
	v_cndmask_b32_e64 v54, 0, 32, vcc
	v_ldexp_f32 v51, v51, v54
	v_log_f32_e32 v51, v51
	s_nop 0
	v_mul_f32_e32 v54, 0x3f317217, v51
	v_fma_f32 v54, v51, s31, -v54
	v_fmac_f32_e32 v54, 0x3377d1cf, v51
	v_fmac_f32_e32 v54, 0x3f317217, v51
	v_cmp_lt_f32_e64 s[18:19], |v51|, s44
	s_nop 1
	v_cndmask_b32_e64 v51, v51, v54, s[18:19]
	v_cndmask_b32_e32 v54, 0, v240, vcc
	v_sub_f32_e32 v51, v51, v54
	v_sub_f32_e32 v116, v50, v51
	v_mul_f32_e64 v51, |v52|, s97
	v_exp_f32_e32 v51, v51
	v_min_f32_e32 v50, 0, v52
	v_mul_f32_e32 v117, 0x3d800000, v116
	v_add_f32_e32 v51, 1.0, v51
	v_cmp_gt_f32_e32 vcc, s45, v51
	s_nop 1
	v_cndmask_b32_e64 v52, 0, 32, vcc
	v_ldexp_f32 v51, v51, v52
	v_log_f32_e32 v51, v51
	s_nop 0
	v_mul_f32_e32 v52, 0x3f317217, v51
	v_fma_f32 v52, v51, s31, -v52
	v_fmac_f32_e32 v52, 0x3377d1cf, v51
	v_fmac_f32_e32 v52, 0x3f317217, v51
	v_cmp_lt_f32_e64 s[18:19], |v51|, s44
	s_nop 1
	v_cndmask_b32_e64 v51, v51, v52, s[18:19]
	v_cndmask_b32_e32 v52, 0, v240, vcc
	v_sub_f32_e32 v51, v51, v52
	v_sub_f32_e32 v114, v50, v51
	v_mul_f32_e64 v51, |v53|, s97
	v_exp_f32_e32 v51, v51
	v_min_f32_e32 v50, 0, v53
	v_mul_f32_e32 v115, 0x3d800000, v114
	v_add_f32_e32 v51, 1.0, v51
	v_cmp_gt_f32_e32 vcc, s45, v51
	s_nop 1
	v_cndmask_b32_e64 v52, 0, 32, vcc
	v_ldexp_f32 v51, v51, v52
	v_log_f32_e32 v51, v51
	s_nop 0
	v_mul_f32_e32 v52, 0x3f317217, v51
	v_fma_f32 v52, v51, s31, -v52
	v_fmac_f32_e32 v52, 0x3377d1cf, v51
	v_fmac_f32_e32 v52, 0x3f317217, v51
	v_cmp_lt_f32_e64 s[18:19], |v51|, s44
	s_nop 1
	v_cndmask_b32_e64 v51, v51, v52, s[18:19]
	v_cndmask_b32_e32 v52, 0, v240, vcc
	v_sub_f32_e32 v51, v51, v52
	v_sub_f32_e32 v112, v50, v51
	ds_read_b128 v[50:53], v103 offset:6480
	ds_read_b128 v[128:131], v103 offset:4432
	v_mul_f32_e32 v113, 0x3d800000, v112
	s_waitcnt lgkmcnt(0)
	v_pk_fma_f32 v[54:55], v[94:95], v[128:129], v[50:51] op_sel_hi:[0,1,1]
	v_pk_fma_f32 v[128:129], v[94:95], v[130:131], v[52:53] op_sel_hi:[0,1,1]
	ds_read_b128 v[50:53], v103 offset:4560
	ds_read_b128 v[168:171], v103 offset:4688
	ds_read_b128 v[172:175], v103 offset:4816
	s_waitcnt lgkmcnt(2)
	v_pk_fma_f32 v[128:129], v[92:93], v[52:53], v[128:129] op_sel_hi:[0,1,1]
	v_pk_fma_f32 v[54:55], v[92:93], v[50:51], v[54:55] op_sel_hi:[0,1,1]
	ds_read_b128 v[50:53], v103 offset:4944
	s_waitcnt lgkmcnt(2)
	v_pk_fma_f32 v[54:55], v[90:91], v[168:169], v[54:55] op_sel_hi:[0,1,1]
	v_pk_fma_f32 v[128:129], v[90:91], v[170:171], v[128:129] op_sel_hi:[0,1,1]
	ds_read_b128 v[168:171], v103 offset:5072
	s_waitcnt lgkmcnt(2)
	v_pk_fma_f32 v[128:129], v[88:89], v[174:175], v[128:129] op_sel_hi:[0,1,1]
	v_pk_fma_f32 v[54:55], v[88:89], v[172:173], v[54:55] op_sel_hi:[0,1,1]
	ds_read_b128 v[172:175], v103 offset:5200
	s_waitcnt lgkmcnt(2)
	v_pk_fma_f32 v[54:55], v[86:87], v[50:51], v[54:55] op_sel_hi:[0,1,1]
	v_pk_fma_f32 v[128:129], v[86:87], v[52:53], v[128:129] op_sel_hi:[0,1,1]
	ds_read_b128 v[50:53], v103 offset:5328
	s_waitcnt lgkmcnt(2)
	v_pk_fma_f32 v[128:129], v[84:85], v[170:171], v[128:129] op_sel_hi:[0,1,1]
	v_pk_fma_f32 v[54:55], v[84:85], v[168:169], v[54:55] op_sel_hi:[0,1,1]
	ds_read_b128 v[168:171], v103 offset:5456
	s_waitcnt lgkmcnt(2)
	v_pk_fma_f32 v[54:55], v[82:83], v[172:173], v[54:55] op_sel_hi:[0,1,1]
	v_pk_fma_f32 v[128:129], v[82:83], v[174:175], v[128:129] op_sel_hi:[0,1,1]
	ds_read_b128 v[172:175], v103 offset:5584
	s_waitcnt lgkmcnt(2)
	v_pk_fma_f32 v[128:129], v[80:81], v[52:53], v[128:129] op_sel_hi:[0,1,1]
	v_pk_fma_f32 v[54:55], v[80:81], v[50:51], v[54:55] op_sel_hi:[0,1,1]
	ds_read_b128 v[50:53], v103 offset:5712
	s_waitcnt lgkmcnt(2)
	v_pk_fma_f32 v[54:55], v[78:79], v[168:169], v[54:55] op_sel_hi:[0,1,1]
	v_pk_fma_f32 v[128:129], v[78:79], v[170:171], v[128:129] op_sel_hi:[0,1,1]
	ds_read_b128 v[168:171], v103 offset:5840
	s_waitcnt lgkmcnt(2)
	v_pk_fma_f32 v[128:129], v[76:77], v[174:175], v[128:129] op_sel_hi:[0,1,1]
	v_pk_fma_f32 v[54:55], v[76:77], v[172:173], v[54:55] op_sel_hi:[0,1,1]
	ds_read_b128 v[172:175], v103 offset:5968
	s_waitcnt lgkmcnt(2)
; #define LAS __attribute__((address_space(3)))
; __device__ __forceinline__ void gla_gates(const bf16* prow, const float* wg, const float* bg, int h, int lane, float (&bc)[32], LAS float* Wst) {
;     ...
;     for (int d4 = 0; d4 < 8; ++d4) { f32x4 z = *(const LAS f32x4*)(Wst + 512 + 4 * d4);
; #pragma unroll
;         for (int r = 0; r < 16; ++r) { const f32x4 w = *(const LAS f32x4*)(Wst + r * 32 + 4 * d4); z += w * glr[r]; }
; #pragma unroll
;         for (int e = 0; e < 4; ++e) bc[4 * d4 + e] = (fminf(z[e], 0.f) - __logf(1.f + __expf(-fabsf(z[e])))) * (1.f / 16.f); }
	v_pk_fma_f32 v[54:55], v[74:75], v[50:51], v[54:55] op_sel_hi:[0,1,1]
	v_pk_fma_f32 v[128:129], v[74:75], v[52:53], v[128:129] op_sel_hi:[0,1,1]
	ds_read_b128 v[50:53], v103 offset:6096
	s_waitcnt lgkmcnt(2)
	v_pk_fma_f32 v[128:129], v[72:73], v[170:171], v[128:129] op_sel_hi:[0,1,1]
	v_pk_fma_f32 v[54:55], v[72:73], v[168:169], v[54:55] op_sel_hi:[0,1,1]
	ds_read_b128 v[168:171], v103 offset:6224
	s_waitcnt lgkmcnt(2)
	v_pk_fma_f32 v[54:55], v[70:71], v[172:173], v[54:55] op_sel_hi:[0,1,1]
	v_pk_fma_f32 v[128:129], v[70:71], v[174:175], v[128:129] op_sel_hi:[0,1,1]
	s_waitcnt lgkmcnt(1)
	v_pk_fma_f32 v[128:129], v[68:69], v[52:53], v[128:129] op_sel_hi:[0,1,1]
	v_pk_fma_f32 v[54:55], v[68:69], v[50:51], v[54:55] op_sel_hi:[0,1,1]
	s_waitcnt lgkmcnt(0)
	v_pk_fma_f32 v[54:55], v[66:67], v[168:169], v[54:55] op_sel_hi:[0,1,1]
	v_pk_fma_f32 v[128:129], v[66:67], v[170:171], v[128:129] op_sel_hi:[0,1,1]
	ds_read_b128 v[50:53], v103 offset:6352
	s_waitcnt lgkmcnt(0)
	v_pk_fma_f32 v[50:51], v[64:65], v[50:51], v[54:55] op_sel_hi:[0,1,1]
	v_min_f32_e32 v54, 0, v50
	v_mul_f32_e64 v50, |v50|, s97
	v_exp_f32_e32 v50, v50
	v_pk_fma_f32 v[52:53], v[64:65], v[52:53], v[128:129] op_sel_hi:[0,1,1]
	v_add_f32_e32 v50, 1.0, v50
	v_cmp_gt_f32_e32 vcc, s45, v50
	s_nop 1
	v_cndmask_b32_e64 v55, 0, 32, vcc
	v_ldexp_f32 v50, v50, v55
	v_log_f32_e32 v50, v50
	s_nop 0
	v_mul_f32_e32 v55, 0x3f317217, v50
	v_fma_f32 v55, v50, s31, -v55
	v_fmac_f32_e32 v55, 0x3377d1cf, v50
	v_fmac_f32_e32 v55, 0x3f317217, v50
	v_cmp_lt_f32_e64 s[18:19], |v50|, s44
	s_nop 1
	v_cndmask_b32_e64 v50, v50, v55, s[18:19]
	v_cndmask_b32_e32 v55, 0, v240, vcc
	v_sub_f32_e32 v50, v50, v55
	v_sub_f32_e32 v142, v54, v50
	v_min_f32_e32 v50, 0, v51
	v_mul_f32_e64 v51, |v51|, s97
	v_exp_f32_e32 v51, v51
	v_mul_f32_e32 v143, 0x3d800000, v142
	v_add_f32_e32 v51, 1.0, v51
	v_cmp_gt_f32_e32 vcc, s45, v51
	s_nop 1
	v_cndmask_b32_e64 v54, 0, 32, vcc
	v_ldexp_f32 v51, v51, v54
	v_log_f32_e32 v51, v51
	s_nop 0
	v_mul_f32_e32 v54, 0x3f317217, v51
	v_fma_f32 v54, v51, s31, -v54
	v_fmac_f32_e32 v54, 0x3377d1cf, v51
	v_fmac_f32_e32 v54, 0x3f317217, v51
	v_cmp_lt_f32_e64 s[18:19], |v51|, s44
	s_nop 1
	v_cndmask_b32_e64 v51, v51, v54, s[18:19]
	v_cndmask_b32_e32 v54, 0, v240, vcc
	v_sub_f32_e32 v51, v51, v54
	v_sub_f32_e32 v140, v50, v51
	v_mul_f32_e64 v51, |v52|, s97
	v_exp_f32_e32 v51, v51
	v_min_f32_e32 v50, 0, v52
	v_mul_f32_e32 v141, 0x3d800000, v140
	v_add_f32_e32 v51, 1.0, v51
	v_cmp_gt_f32_e32 vcc, s45, v51
	s_nop 1
	v_cndmask_b32_e64 v52, 0, 32, vcc
	v_ldexp_f32 v51, v51, v52
	v_log_f32_e32 v51, v51
	s_nop 0
	v_mul_f32_e32 v52, 0x3f317217, v51
	v_fma_f32 v52, v51, s31, -v52
	v_fmac_f32_e32 v52, 0x3377d1cf, v51
	v_fmac_f32_e32 v52, 0x3f317217, v51
	v_cmp_lt_f32_e64 s[18:19], |v51|, s44
	s_nop 1
	v_cndmask_b32_e64 v51, v51, v52, s[18:19]
	v_cndmask_b32_e32 v52, 0, v240, vcc
	v_sub_f32_e32 v51, v51, v52
	v_sub_f32_e32 v138, v50, v51
	v_mul_f32_e64 v51, |v53|, s97
	v_exp_f32_e32 v51, v51
	v_min_f32_e32 v50, 0, v53
	v_mul_f32_e32 v139, 0x3d800000, v138
	v_add_f32_e32 v51, 1.0, v51
	v_cmp_gt_f32_e32 vcc, s45, v51
	s_nop 1
	v_cndmask_b32_e64 v52, 0, 32, vcc
	v_ldexp_f32 v51, v51, v52
	v_log_f32_e32 v51, v51
	s_nop 0
	v_mul_f32_e32 v52, 0x3f317217, v51
	v_fma_f32 v52, v51, s31, -v52
	v_fmac_f32_e32 v52, 0x3377d1cf, v51
	v_fmac_f32_e32 v52, 0x3f317217, v51
	v_cmp_lt_f32_e64 s[18:19], |v51|, s44
	s_nop 1
	v_cndmask_b32_e64 v51, v51, v52, s[18:19]
	v_cndmask_b32_e32 v52, 0, v240, vcc
	v_sub_f32_e32 v51, v51, v52
	v_sub_f32_e32 v136, v50, v51
	ds_read_b128 v[50:53], v103 offset:6496
	ds_read_b128 v[128:131], v103 offset:4448
	v_mul_f32_e32 v137, 0x3d800000, v136
	s_waitcnt lgkmcnt(0)
	v_pk_fma_f32 v[54:55], v[94:95], v[128:129], v[50:51] op_sel_hi:[0,1,1]
	v_pk_fma_f32 v[128:129], v[94:95], v[130:131], v[52:53] op_sel_hi:[0,1,1]
	ds_read_b128 v[50:53], v103 offset:4576
	ds_read_b128 v[168:171], v103 offset:4704
	ds_read_b128 v[172:175], v103 offset:4832
	s_waitcnt lgkmcnt(2)
	v_pk_fma_f32 v[128:129], v[92:93], v[52:53], v[128:129] op_sel_hi:[0,1,1]
	v_pk_fma_f32 v[54:55], v[92:93], v[50:51], v[54:55] op_sel_hi:[0,1,1]
	ds_read_b128 v[50:53], v103 offset:4960
	s_waitcnt lgkmcnt(2)
	v_pk_fma_f32 v[54:55], v[90:91], v[168:169], v[54:55] op_sel_hi:[0,1,1]
	v_pk_fma_f32 v[128:129], v[90:91], v[170:171], v[128:129] op_sel_hi:[0,1,1]
	ds_read_b128 v[168:171], v103 offset:5088
	s_waitcnt lgkmcnt(2)
	v_pk_fma_f32 v[128:129], v[88:89], v[174:175], v[128:129] op_sel_hi:[0,1,1]
	v_pk_fma_f32 v[54:55], v[88:89], v[172:173], v[54:55] op_sel_hi:[0,1,1]
	ds_read_b128 v[172:175], v103 offset:5216
	s_waitcnt lgkmcnt(2)
	v_pk_fma_f32 v[54:55], v[86:87], v[50:51], v[54:55] op_sel_hi:[0,1,1]
	v_pk_fma_f32 v[128:129], v[86:87], v[52:53], v[128:129] op_sel_hi:[0,1,1]
	ds_read_b128 v[50:53], v103 offset:5344
	s_waitcnt lgkmcnt(2)
	v_pk_fma_f32 v[128:129], v[84:85], v[170:171], v[128:129] op_sel_hi:[0,1,1]
	v_pk_fma_f32 v[54:55], v[84:85], v[168:169], v[54:55] op_sel_hi:[0,1,1]
	ds_read_b128 v[168:171], v103 offset:5472
	s_waitcnt lgkmcnt(2)
	v_pk_fma_f32 v[54:55], v[82:83], v[172:173], v[54:55] op_sel_hi:[0,1,1]
	v_pk_fma_f32 v[128:129], v[82:83], v[174:175], v[128:129] op_sel_hi:[0,1,1]
	ds_read_b128 v[172:175], v103 offset:5600
	s_waitcnt lgkmcnt(2)
	v_pk_fma_f32 v[128:129], v[80:81], v[52:53], v[128:129] op_sel_hi:[0,1,1]
	v_pk_fma_f32 v[54:55], v[80:81], v[50:51], v[54:55] op_sel_hi:[0,1,1]
	ds_read_b128 v[50:53], v103 offset:5728
	s_waitcnt lgkmcnt(2)
	v_pk_fma_f32 v[54:55], v[78:79], v[168:169], v[54:55] op_sel_hi:[0,1,1]
	v_pk_fma_f32 v[128:129], v[78:79], v[170:171], v[128:129] op_sel_hi:[0,1,1]
	ds_read_b128 v[168:171], v103 offset:5856
	s_waitcnt lgkmcnt(2)
; #define LAS __attribute__((address_space(3)))
; __device__ __forceinline__ void gla_gates(const bf16* prow, const float* wg, const float* bg, int h, int lane, float (&bc)[32], LAS float* Wst) {
;     ...
;     for (int d4 = 0; d4 < 8; ++d4) { f32x4 z = *(const LAS f32x4*)(Wst + 512 + 4 * d4);
; #pragma unroll
;         for (int r = 0; r < 16; ++r) { const f32x4 w = *(const LAS f32x4*)(Wst + r * 32 + 4 * d4); z += w * glr[r]; }
; #pragma unroll
;         for (int e = 0; e < 4; ++e) bc[4 * d4 + e] = (fminf(z[e], 0.f) - __logf(1.f + __expf(-fabsf(z[e])))) * (1.f / 16.f); }
	v_pk_fma_f32 v[128:129], v[76:77], v[174:175], v[128:129] op_sel_hi:[0,1,1]
	v_pk_fma_f32 v[54:55], v[76:77], v[172:173], v[54:55] op_sel_hi:[0,1,1]
	ds_read_b128 v[172:175], v103 offset:5984
	s_waitcnt lgkmcnt(2)
	v_pk_fma_f32 v[54:55], v[74:75], v[50:51], v[54:55] op_sel_hi:[0,1,1]
	v_pk_fma_f32 v[128:129], v[74:75], v[52:53], v[128:129] op_sel_hi:[0,1,1]
	ds_read_b128 v[50:53], v103 offset:6112
	s_waitcnt lgkmcnt(2)
	v_pk_fma_f32 v[128:129], v[72:73], v[170:171], v[128:129] op_sel_hi:[0,1,1]
	v_pk_fma_f32 v[54:55], v[72:73], v[168:169], v[54:55] op_sel_hi:[0,1,1]
	ds_read_b128 v[168:171], v103 offset:6240
	s_waitcnt lgkmcnt(2)
	v_pk_fma_f32 v[54:55], v[70:71], v[172:173], v[54:55] op_sel_hi:[0,1,1]
	v_pk_fma_f32 v[128:129], v[70:71], v[174:175], v[128:129] op_sel_hi:[0,1,1]
	s_waitcnt lgkmcnt(1)
	v_pk_fma_f32 v[128:129], v[68:69], v[52:53], v[128:129] op_sel_hi:[0,1,1]
	v_pk_fma_f32 v[54:55], v[68:69], v[50:51], v[54:55] op_sel_hi:[0,1,1]
	s_waitcnt lgkmcnt(0)
	v_pk_fma_f32 v[54:55], v[66:67], v[168:169], v[54:55] op_sel_hi:[0,1,1]
	v_pk_fma_f32 v[128:129], v[66:67], v[170:171], v[128:129] op_sel_hi:[0,1,1]
	ds_read_b128 v[50:53], v103 offset:6368
	s_waitcnt lgkmcnt(0)
	v_pk_fma_f32 v[50:51], v[64:65], v[50:51], v[54:55] op_sel_hi:[0,1,1]
	v_min_f32_e32 v54, 0, v50
	v_mul_f32_e64 v50, |v50|, s97
	v_exp_f32_e32 v50, v50
	v_pk_fma_f32 v[52:53], v[64:65], v[52:53], v[128:129] op_sel_hi:[0,1,1]
	v_add_f32_e32 v50, 1.0, v50
	v_cmp_gt_f32_e32 vcc, s45, v50
	s_nop 1
	v_cndmask_b32_e64 v55, 0, 32, vcc
	v_ldexp_f32 v50, v50, v55
	v_log_f32_e32 v50, v50
	s_nop 0
	v_mul_f32_e32 v55, 0x3f317217, v50
	v_fma_f32 v55, v50, s31, -v55
	v_fmac_f32_e32 v55, 0x3377d1cf, v50
	v_fmac_f32_e32 v55, 0x3f317217, v50
	v_cmp_lt_f32_e64 s[18:19], |v50|, s44
	s_nop 1
	v_cndmask_b32_e64 v50, v50, v55, s[18:19]
	v_cndmask_b32_e32 v55, 0, v240, vcc
	v_sub_f32_e32 v50, v50, v55
	v_sub_f32_e32 v134, v54, v50
	v_min_f32_e32 v50, 0, v51
	v_mul_f32_e64 v51, |v51|, s97
	v_exp_f32_e32 v51, v51
	v_mul_f32_e32 v135, 0x3d800000, v134
	v_add_f32_e32 v51, 1.0, v51
	v_cmp_gt_f32_e32 vcc, s45, v51
	s_nop 1
	v_cndmask_b32_e64 v54, 0, 32, vcc
	v_ldexp_f32 v51, v51, v54
	v_log_f32_e32 v51, v51
	s_nop 0
	v_mul_f32_e32 v54, 0x3f317217, v51
	v_fma_f32 v54, v51, s31, -v54
	v_fmac_f32_e32 v54, 0x3377d1cf, v51
	v_fmac_f32_e32 v54, 0x3f317217, v51
	v_cmp_lt_f32_e64 s[18:19], |v51|, s44
	s_nop 1
	v_cndmask_b32_e64 v51, v51, v54, s[18:19]
	v_cndmask_b32_e32 v54, 0, v240, vcc
	v_sub_f32_e32 v51, v51, v54
	v_sub_f32_e32 v132, v50, v51
	v_mul_f32_e64 v51, |v52|, s97
	v_exp_f32_e32 v51, v51
	v_min_f32_e32 v50, 0, v52
	v_mul_f32_e32 v133, 0x3d800000, v132
	v_add_f32_e32 v51, 1.0, v51
	v_cmp_gt_f32_e32 vcc, s45, v51
	s_nop 1
	v_cndmask_b32_e64 v52, 0, 32, vcc
	v_ldexp_f32 v51, v51, v52
	v_log_f32_e32 v51, v51
	s_nop 0
	v_mul_f32_e32 v52, 0x3f317217, v51
	v_fma_f32 v52, v51, s31, -v52
	v_fmac_f32_e32 v52, 0x3377d1cf, v51
	v_fmac_f32_e32 v52, 0x3f317217, v51
	v_cmp_lt_f32_e64 s[18:19], |v51|, s44
	s_nop 1
	v_cndmask_b32_e64 v51, v51, v52, s[18:19]
	v_cndmask_b32_e32 v52, 0, v240, vcc
	v_sub_f32_e32 v51, v51, v52
	v_sub_f32_e32 v130, v50, v51
	v_mul_f32_e64 v51, |v53|, s97
	v_exp_f32_e32 v51, v51
	v_min_f32_e32 v50, 0, v53
	v_mul_f32_e32 v131, 0x3d800000, v130
	v_add_f32_e32 v51, 1.0, v51
	v_cmp_gt_f32_e32 vcc, s45, v51
	s_nop 1
	v_cndmask_b32_e64 v52, 0, 32, vcc
	v_ldexp_f32 v51, v51, v52
	v_log_f32_e32 v51, v51
	s_nop 0
	v_mul_f32_e32 v52, 0x3f317217, v51
	v_fma_f32 v52, v51, s31, -v52
	v_fmac_f32_e32 v52, 0x3377d1cf, v51
	v_fmac_f32_e32 v52, 0x3f317217, v51
	v_cmp_lt_f32_e64 s[18:19], |v51|, s44
	s_nop 1
	v_cndmask_b32_e64 v51, v51, v52, s[18:19]
	v_cndmask_b32_e32 v52, 0, v240, vcc
	v_sub_f32_e32 v51, v51, v52
	v_sub_f32_e32 v128, v50, v51
	ds_read_b128 v[50:53], v103 offset:6512
	ds_read_b128 v[144:147], v103 offset:4464
	v_mul_f32_e32 v129, 0x3d800000, v128
	s_waitcnt lgkmcnt(0)
	v_pk_fma_f32 v[54:55], v[94:95], v[144:145], v[50:51] op_sel_hi:[0,1,1]
	v_pk_fma_f32 v[144:145], v[94:95], v[146:147], v[52:53] op_sel_hi:[0,1,1]
	ds_read_b128 v[50:53], v103 offset:4592
	ds_read_b128 v[168:171], v103 offset:4720
	ds_read_b128 v[172:175], v103 offset:4848
	s_waitcnt lgkmcnt(2)
	v_pk_fma_f32 v[144:145], v[92:93], v[52:53], v[144:145] op_sel_hi:[0,1,1]
	v_pk_fma_f32 v[54:55], v[92:93], v[50:51], v[54:55] op_sel_hi:[0,1,1]
	ds_read_b128 v[50:53], v103 offset:4976
	s_waitcnt lgkmcnt(2)
	v_pk_fma_f32 v[54:55], v[90:91], v[168:169], v[54:55] op_sel_hi:[0,1,1]
	v_pk_fma_f32 v[144:145], v[90:91], v[170:171], v[144:145] op_sel_hi:[0,1,1]
	ds_read_b128 v[168:171], v103 offset:5104
	s_waitcnt lgkmcnt(2)
	v_pk_fma_f32 v[144:145], v[88:89], v[174:175], v[144:145] op_sel_hi:[0,1,1]
	v_pk_fma_f32 v[54:55], v[88:89], v[172:173], v[54:55] op_sel_hi:[0,1,1]
	ds_read_b128 v[172:175], v103 offset:5232
	s_waitcnt lgkmcnt(2)
	v_pk_fma_f32 v[54:55], v[86:87], v[50:51], v[54:55] op_sel_hi:[0,1,1]
	v_pk_fma_f32 v[144:145], v[86:87], v[52:53], v[144:145] op_sel_hi:[0,1,1]
	ds_read_b128 v[50:53], v103 offset:5360
	s_waitcnt lgkmcnt(2)
	v_pk_fma_f32 v[144:145], v[84:85], v[170:171], v[144:145] op_sel_hi:[0,1,1]
	v_pk_fma_f32 v[54:55], v[84:85], v[168:169], v[54:55] op_sel_hi:[0,1,1]
	ds_read_b128 v[168:171], v103 offset:5488
	s_waitcnt lgkmcnt(2)
	v_pk_fma_f32 v[54:55], v[82:83], v[172:173], v[54:55] op_sel_hi:[0,1,1]
	v_pk_fma_f32 v[144:145], v[82:83], v[174:175], v[144:145] op_sel_hi:[0,1,1]
	ds_read_b128 v[172:175], v103 offset:5616
	s_waitcnt lgkmcnt(2)
	v_pk_fma_f32 v[144:145], v[80:81], v[52:53], v[144:145] op_sel_hi:[0,1,1]
	v_pk_fma_f32 v[54:55], v[80:81], v[50:51], v[54:55] op_sel_hi:[0,1,1]
	ds_read_b128 v[50:53], v103 offset:5744
	s_waitcnt lgkmcnt(2)
; #define LAS __attribute__((address_space(3)))
; __device__ __forceinline__ void gla_gates(const bf16* prow, const float* wg, const float* bg, int h, int lane, float (&bc)[32], LAS float* Wst) {
;     ...
;     for (int d4 = 0; d4 < 8; ++d4) { f32x4 z = *(const LAS f32x4*)(Wst + 512 + 4 * d4);
; #pragma unroll
;         for (int r = 0; r < 16; ++r) { const f32x4 w = *(const LAS f32x4*)(Wst + r * 32 + 4 * d4); z += w * glr[r]; }
; #pragma unroll
;         for (int e = 0; e < 4; ++e) bc[4 * d4 + e] = (fminf(z[e], 0.f) - __logf(1.f + __expf(-fabsf(z[e])))) * (1.f / 16.f); }
;     ...
;     for (int d = 0; d < 32; ++d) { float v = bc[d];
; #pragma unroll
;         for (int off = 1; off < 64; off <<= 1) { const float t = __shfl_up(v, off); if (lane >= off) v += t; }
;         bc[d] = v; }
	v_pk_fma_f32 v[54:55], v[78:79], v[168:169], v[54:55] op_sel_hi:[0,1,1]
	v_pk_fma_f32 v[144:145], v[78:79], v[170:171], v[144:145] op_sel_hi:[0,1,1]
	ds_read_b128 v[168:171], v103 offset:5872
	s_waitcnt lgkmcnt(2)
	v_pk_fma_f32 v[144:145], v[76:77], v[174:175], v[144:145] op_sel_hi:[0,1,1]
	v_pk_fma_f32 v[54:55], v[76:77], v[172:173], v[54:55] op_sel_hi:[0,1,1]
	ds_read_b128 v[172:175], v103 offset:6000
	s_waitcnt lgkmcnt(2)
	v_pk_fma_f32 v[54:55], v[74:75], v[50:51], v[54:55] op_sel_hi:[0,1,1]
	v_pk_fma_f32 v[144:145], v[74:75], v[52:53], v[144:145] op_sel_hi:[0,1,1]
	ds_read_b128 v[50:53], v103 offset:6128
	s_waitcnt lgkmcnt(2)
	v_pk_fma_f32 v[144:145], v[72:73], v[170:171], v[144:145] op_sel_hi:[0,1,1]
	v_pk_fma_f32 v[54:55], v[72:73], v[168:169], v[54:55] op_sel_hi:[0,1,1]
	s_waitcnt lgkmcnt(1)
	v_pk_fma_f32 v[54:55], v[70:71], v[172:173], v[54:55] op_sel_hi:[0,1,1]
	v_pk_fma_f32 v[144:145], v[70:71], v[174:175], v[144:145] op_sel_hi:[0,1,1]
	s_waitcnt lgkmcnt(0)
	v_pk_fma_f32 v[144:145], v[68:69], v[52:53], v[144:145] op_sel_hi:[0,1,1]
	v_pk_fma_f32 v[54:55], v[68:69], v[50:51], v[54:55] op_sel_hi:[0,1,1]
	ds_read_b128 v[50:53], v103 offset:6256
	s_waitcnt lgkmcnt(0)
	v_pk_fma_f32 v[54:55], v[66:67], v[50:51], v[54:55] op_sel_hi:[0,1,1]
	v_pk_fma_f32 v[144:145], v[66:67], v[52:53], v[144:145] op_sel_hi:[0,1,1]
	ds_read_b128 v[50:53], v103 offset:6384
	s_waitcnt lgkmcnt(0)
	s_waitcnt lgkmcnt(0)
	v_pk_fma_f32 v[50:51], v[64:65], v[50:51], v[54:55] op_sel_hi:[0,1,1]
	v_min_f32_e32 v54, 0, v50
	v_mul_f32_e64 v50, |v50|, s97
	v_exp_f32_e32 v50, v50
	v_pk_fma_f32 v[52:53], v[64:65], v[52:53], v[144:145] op_sel_hi:[0,1,1]
	v_lshlrev_b32_e32 v145, 16, v44
	v_add_f32_e32 v50, 1.0, v50
	v_cmp_gt_f32_e32 vcc, s45, v50
	s_nop 1
	v_cndmask_b32_e64 v55, 0, 32, vcc
	v_ldexp_f32 v50, v50, v55
	v_log_f32_e32 v50, v50
	s_nop 0
	v_mul_f32_e32 v55, 0x3f317217, v50
	v_fma_f32 v55, v50, s31, -v55
	v_fmac_f32_e32 v55, 0x3377d1cf, v50
	v_fmac_f32_e32 v55, 0x3f317217, v50
	v_cmp_lt_f32_e64 s[18:19], |v50|, s44
	s_nop 1
	v_cndmask_b32_e64 v50, v50, v55, s[18:19]
	v_cndmask_b32_e32 v55, 0, v240, vcc
	v_sub_f32_e32 v50, v50, v55
	v_sub_f32_e32 v103, v54, v50
	v_min_f32_e32 v50, 0, v51
	v_mul_f32_e64 v51, |v51|, s97
	v_exp_f32_e32 v51, v51
	v_mul_f32_e32 v144, 0x3d800000, v103
	v_add_f32_e32 v51, 1.0, v51
	v_cmp_gt_f32_e32 vcc, s45, v51
	s_nop 1
	v_cndmask_b32_e64 v54, 0, 32, vcc
	v_ldexp_f32 v51, v51, v54
	v_log_f32_e32 v51, v51
	s_nop 0
	v_mul_f32_e32 v54, 0x3f317217, v51
	v_fma_f32 v54, v51, s31, -v54
	v_fmac_f32_e32 v54, 0x3377d1cf, v51
	v_fmac_f32_e32 v54, 0x3f317217, v51
	v_cmp_lt_f32_e64 s[18:19], |v51|, s44
	s_nop 1
	v_cndmask_b32_e64 v51, v51, v54, s[18:19]
	v_cndmask_b32_e32 v54, 0, v240, vcc
	v_sub_f32_e32 v51, v51, v54
	v_sub_f32_e32 v82, v50, v51
	v_mul_f32_e64 v51, |v52|, s97
	v_exp_f32_e32 v51, v51
	v_min_f32_e32 v50, 0, v52
	v_mul_f32_e32 v84, 0x3d800000, v82
	v_add_f32_e32 v51, 1.0, v51
	v_cmp_gt_f32_e32 vcc, s45, v51
	s_nop 1
	v_cndmask_b32_e64 v52, 0, 32, vcc
	v_ldexp_f32 v51, v51, v52
	v_log_f32_e32 v51, v51
	s_nop 0
	v_mul_f32_e32 v52, 0x3f317217, v51
	v_fma_f32 v52, v51, s31, -v52
	v_fmac_f32_e32 v52, 0x3377d1cf, v51
	v_fmac_f32_e32 v52, 0x3f317217, v51
	v_cmp_lt_f32_e64 s[18:19], |v51|, s44
	s_nop 1
	v_cndmask_b32_e64 v51, v51, v52, s[18:19]
	v_cndmask_b32_e32 v52, 0, v240, vcc
	v_sub_f32_e32 v51, v51, v52
	v_sub_f32_e32 v76, v50, v51
	v_mul_f32_e64 v51, |v53|, s97
	v_exp_f32_e32 v51, v51
	v_min_f32_e32 v50, 0, v53
	v_mul_f32_e32 v78, 0x3d800000, v76
	v_add_f32_e32 v51, 1.0, v51
	v_cmp_gt_f32_e32 vcc, s45, v51
	s_nop 1
	v_cndmask_b32_e64 v52, 0, 32, vcc
	v_ldexp_f32 v51, v51, v52
	v_log_f32_e32 v51, v51
	s_nop 0
	v_mul_f32_e32 v52, 0x3f317217, v51
	v_fma_f32 v52, v51, s31, -v52
	v_fmac_f32_e32 v52, 0x3377d1cf, v51
	v_fmac_f32_e32 v52, 0x3f317217, v51
	v_cmp_lt_f32_e64 s[18:19], |v51|, s44
	s_nop 1
	v_cndmask_b32_e64 v51, v51, v52, s[18:19]
	v_cndmask_b32_e32 v52, 0, v240, vcc
	v_sub_f32_e32 v51, v51, v52
	v_sub_f32_e32 v70, v50, v51
	v_and_b32_e32 v50, 64, v241
	v_add_u32_e32 v51, -1, v241
	v_cmp_lt_i32_e32 vcc, v51, v50
	v_add_u32_e32 v52, -2, v241
	v_mul_f32_e32 v72, 0x3d800000, v70
	v_cndmask_b32_e32 v51, v51, v241, vcc
	v_lshlrev_b32_e32 v88, 2, v51
	ds_bpermute_b32 v51, v88, v102
	v_cmp_lt_i32_e32 vcc, v52, v50
	s_waitcnt lgkmcnt(0)
	v_fmac_f32_e32 v51, 0x3d800000, v101
	v_cndmask_b32_e32 v52, v52, v241, vcc
	v_cndmask_b32_e64 v51, v51, v102, s[6:7]
	v_lshlrev_b32_e32 v90, 2, v52
	ds_bpermute_b32 v52, v90, v51
	s_waitcnt lgkmcnt(0)
	v_add_f32_e32 v52, v51, v52
	v_cndmask_b32_e64 v51, v52, v51, s[8:9]
	v_add_u32_e32 v52, -4, v241
	v_cmp_lt_i32_e32 vcc, v52, v50
	s_nop 1
	v_cndmask_b32_e32 v52, v52, v241, vcc
	v_lshlrev_b32_e32 v94, 2, v52
	ds_bpermute_b32 v52, v94, v51
	s_waitcnt lgkmcnt(0)
	v_add_f32_e32 v52, v51, v52
	v_cndmask_b32_e64 v51, v52, v51, s[10:11]
	v_add_u32_e32 v52, -8, v241
	v_cmp_lt_i32_e32 vcc, v52, v50
	s_nop 1
	v_cndmask_b32_e32 v52, v52, v241, vcc
	v_lshlrev_b32_e32 v101, 2, v52
	ds_bpermute_b32 v52, v101, v51
	s_waitcnt lgkmcnt(0)
	v_add_f32_e32 v52, v51, v52
	v_cndmask_b32_e64 v51, v52, v51, s[12:13]
	v_add_u32_e32 v52, -16, v241
	v_cmp_lt_i32_e32 vcc, v52, v50
	s_nop 1
	v_cndmask_b32_e32 v52, v52, v241, vcc
	v_lshlrev_b32_e32 v102, 2, v52
	ds_bpermute_b32 v52, v102, v51
	s_waitcnt lgkmcnt(0)
	v_add_f32_e32 v52, v51, v52
	v_cndmask_b32_e64 v51, v52, v51, s[14:15]
	v_subrev_u32_e32 v52, 32, v241
	v_cmp_lt_i32_e32 vcc, v52, v50
	s_nop 1
	v_cndmask_b32_e32 v50, v52, v241, vcc
	v_lshlrev_b32_e32 v92, 2, v50
	ds_bpermute_b32 v50, v92, v51
	s_waitcnt lgkmcnt(0)
; __device__ __forceinline__ void gla_gates(const bf16* prow, const float* wg, const float* bg, int h, int lane, float (&bc)[32], LAS float* Wst) {
;     ...
;     for (int d = 0; d < 32; ++d) { float v = bc[d];
; #pragma unroll
;         for (int off = 1; off < 64; off <<= 1) { const float t = __shfl_up(v, off); if (lane >= off) v += t; }
;         bc[d] = v; }
	v_add_f32_e32 v50, v51, v50
	v_cndmask_b32_e64 v74, v50, v51, s[4:5]
	ds_bpermute_b32 v154, v88, v100
	ds_bpermute_b32 v155, v88, v98
	ds_bpermute_b32 v156, v88, v93
	ds_bpermute_b32 v157, v88, v111
	ds_bpermute_b32 v158, v88, v109
	ds_bpermute_b32 v159, v88, v107
	ds_bpermute_b32 v160, v88, v105
	s_waitcnt lgkmcnt(6)
	v_fmac_f32_e32 v154, 0x3d800000, v99
	v_cndmask_b32_e64 v161, v154, v100, s[6:7]
	s_waitcnt lgkmcnt(5)
	v_fmac_f32_e32 v155, 0x3d800000, v95
	v_cndmask_b32_e64 v162, v155, v98, s[6:7]
	s_waitcnt lgkmcnt(4)
	v_fmac_f32_e32 v156, 0x3d800000, v91
	v_cndmask_b32_e64 v163, v156, v93, s[6:7]
	s_waitcnt lgkmcnt(3)
	v_fmac_f32_e32 v157, 0x3d800000, v110
	v_cndmask_b32_e64 v164, v157, v111, s[6:7]
	s_waitcnt lgkmcnt(2)
	v_fmac_f32_e32 v158, 0x3d800000, v108
	v_cndmask_b32_e64 v165, v158, v109, s[6:7]
	s_waitcnt lgkmcnt(1)
	v_fmac_f32_e32 v159, 0x3d800000, v106
	v_cndmask_b32_e64 v166, v159, v107, s[6:7]
	s_waitcnt lgkmcnt(0)
	v_fmac_f32_e32 v160, 0x3d800000, v104
	v_cndmask_b32_e64 v167, v160, v105, s[6:7]
	ds_bpermute_b32 v154, v90, v161
	ds_bpermute_b32 v155, v90, v162
	ds_bpermute_b32 v156, v90, v163
	ds_bpermute_b32 v157, v90, v164
	ds_bpermute_b32 v158, v90, v165
	ds_bpermute_b32 v159, v90, v166
	ds_bpermute_b32 v160, v90, v167
	s_waitcnt lgkmcnt(6)
	v_add_f32_e32 v154, v161, v154
	v_cndmask_b32_e64 v161, v154, v161, s[8:9]
	s_waitcnt lgkmcnt(5)
	v_add_f32_e32 v155, v162, v155
	v_cndmask_b32_e64 v162, v155, v162, s[8:9]
	s_waitcnt lgkmcnt(4)
	v_add_f32_e32 v156, v163, v156
	v_cndmask_b32_e64 v163, v156, v163, s[8:9]
	s_waitcnt lgkmcnt(3)
	v_add_f32_e32 v157, v164, v157
	v_cndmask_b32_e64 v164, v157, v164, s[8:9]
	s_waitcnt lgkmcnt(2)
	v_add_f32_e32 v158, v165, v158
	v_cndmask_b32_e64 v165, v158, v165, s[8:9]
	s_waitcnt lgkmcnt(1)
	v_add_f32_e32 v159, v166, v159
	v_cndmask_b32_e64 v166, v159, v166, s[8:9]
	s_waitcnt lgkmcnt(0)
	v_add_f32_e32 v160, v167, v160
	v_cndmask_b32_e64 v167, v160, v167, s[8:9]
	ds_bpermute_b32 v154, v94, v161
	ds_bpermute_b32 v155, v94, v162
	ds_bpermute_b32 v156, v94, v163
	ds_bpermute_b32 v157, v94, v164
	ds_bpermute_b32 v158, v94, v165
	ds_bpermute_b32 v159, v94, v166
	ds_bpermute_b32 v160, v94, v167
	s_waitcnt lgkmcnt(6)
	v_add_f32_e32 v154, v161, v154
	v_cndmask_b32_e64 v161, v154, v161, s[10:11]
	s_waitcnt lgkmcnt(5)
	v_add_f32_e32 v155, v162, v155
	v_cndmask_b32_e64 v162, v155, v162, s[10:11]
	s_waitcnt lgkmcnt(4)
	v_add_f32_e32 v156, v163, v156
	v_cndmask_b32_e64 v163, v156, v163, s[10:11]
	s_waitcnt lgkmcnt(3)
	v_add_f32_e32 v157, v164, v157
	v_cndmask_b32_e64 v164, v157, v164, s[10:11]
	s_waitcnt lgkmcnt(2)
	v_add_f32_e32 v158, v165, v158
	v_cndmask_b32_e64 v165, v158, v165, s[10:11]
	s_waitcnt lgkmcnt(1)
	v_add_f32_e32 v159, v166, v159
	v_cndmask_b32_e64 v166, v159, v166, s[10:11]
	s_waitcnt lgkmcnt(0)
	v_add_f32_e32 v160, v167, v160
	v_cndmask_b32_e64 v167, v160, v167, s[10:11]
	ds_bpermute_b32 v154, v101, v161
	ds_bpermute_b32 v155, v101, v162
	ds_bpermute_b32 v156, v101, v163
	ds_bpermute_b32 v157, v101, v164
	ds_bpermute_b32 v158, v101, v165
	ds_bpermute_b32 v159, v101, v166
	ds_bpermute_b32 v160, v101, v167
	s_waitcnt lgkmcnt(6)
	v_add_f32_e32 v154, v161, v154
	v_cndmask_b32_e64 v161, v154, v161, s[12:13]
	s_waitcnt lgkmcnt(5)
	v_add_f32_e32 v155, v162, v155
	v_cndmask_b32_e64 v162, v155, v162, s[12:13]
	s_waitcnt lgkmcnt(4)
	v_add_f32_e32 v156, v163, v156
	v_cndmask_b32_e64 v163, v156, v163, s[12:13]
	s_waitcnt lgkmcnt(3)
	v_add_f32_e32 v157, v164, v157
	v_cndmask_b32_e64 v164, v157, v164, s[12:13]
	s_waitcnt lgkmcnt(2)
	v_add_f32_e32 v158, v165, v158
	v_cndmask_b32_e64 v165, v158, v165, s[12:13]
	s_waitcnt lgkmcnt(1)
	v_add_f32_e32 v159, v166, v159
	v_cndmask_b32_e64 v166, v159, v166, s[12:13]
	s_waitcnt lgkmcnt(0)
	v_add_f32_e32 v160, v167, v160
	v_cndmask_b32_e64 v167, v160, v167, s[12:13]
	ds_bpermute_b32 v154, v102, v161
	ds_bpermute_b32 v155, v102, v162
	ds_bpermute_b32 v156, v102, v163
	ds_bpermute_b32 v157, v102, v164
	ds_bpermute_b32 v158, v102, v165
	ds_bpermute_b32 v159, v102, v166
	ds_bpermute_b32 v160, v102, v167
	s_waitcnt lgkmcnt(6)
	v_add_f32_e32 v154, v161, v154
	v_cndmask_b32_e64 v161, v154, v161, s[14:15]
	s_waitcnt lgkmcnt(5)
	v_add_f32_e32 v155, v162, v155
	v_cndmask_b32_e64 v162, v155, v162, s[14:15]
	s_waitcnt lgkmcnt(4)
	v_add_f32_e32 v156, v163, v156
	v_cndmask_b32_e64 v163, v156, v163, s[14:15]
	s_waitcnt lgkmcnt(3)
	v_add_f32_e32 v157, v164, v157
	v_cndmask_b32_e64 v164, v157, v164, s[14:15]
	s_waitcnt lgkmcnt(2)
	v_add_f32_e32 v158, v165, v158
	v_cndmask_b32_e64 v165, v158, v165, s[14:15]
	s_waitcnt lgkmcnt(1)
	v_add_f32_e32 v159, v166, v159
	v_cndmask_b32_e64 v166, v159, v166, s[14:15]
	s_waitcnt lgkmcnt(0)
	v_add_f32_e32 v160, v167, v160
	v_cndmask_b32_e64 v167, v160, v167, s[14:15]
	ds_bpermute_b32 v154, v92, v161
	ds_bpermute_b32 v155, v92, v162
	ds_bpermute_b32 v156, v92, v163
	ds_bpermute_b32 v157, v92, v164
	ds_bpermute_b32 v158, v92, v165
	ds_bpermute_b32 v159, v92, v166
	ds_bpermute_b32 v160, v92, v167
	s_waitcnt lgkmcnt(6)
	v_add_f32_e32 v51, v161, v154
	v_cndmask_b32_e64 v80, v51, v161, s[4:5]
	s_waitcnt lgkmcnt(5)
	v_add_f32_e32 v52, v162, v155
	v_cndmask_b32_e64 v95, v52, v162, s[4:5]
	s_waitcnt lgkmcnt(4)
	v_add_f32_e32 v53, v163, v156
	v_cndmask_b32_e64 v93, v53, v163, s[4:5]
	s_waitcnt lgkmcnt(3)
	v_add_f32_e32 v54, v164, v157
	v_cndmask_b32_e64 v98, v54, v164, s[4:5]
	s_waitcnt lgkmcnt(2)
	v_add_f32_e32 v55, v165, v158
	v_cndmask_b32_e64 v99, v55, v165, s[4:5]
	s_waitcnt lgkmcnt(1)
	v_add_f32_e32 v64, v166, v159
	v_cndmask_b32_e64 v100, v64, v166, s[4:5]
	s_waitcnt lgkmcnt(0)
; __device__ __forceinline__ void gla_gates(const bf16* prow, const float* wg, const float* bg, int h, int lane, float (&bc)[32], LAS float* Wst) {
;     ...
;     for (int d = 0; d < 32; ++d) { float v = bc[d];
; #pragma unroll
;         for (int off = 1; off < 64; off <<= 1) { const float t = __shfl_up(v, off); if (lane >= off) v += t; }
;         bc[d] = v; }
	v_add_f32_e32 v66, v167, v160
	v_cndmask_b32_e64 v105, v66, v167, s[4:5]
	ds_bpermute_b32 v154, v88, v97
	ds_bpermute_b32 v155, v88, v61
	ds_bpermute_b32 v156, v88, v59
	ds_bpermute_b32 v157, v88, v57
	ds_bpermute_b32 v158, v88, v127
	ds_bpermute_b32 v159, v88, v125
	ds_bpermute_b32 v160, v88, v123
	s_waitcnt lgkmcnt(6)
	v_fmac_f32_e32 v154, 0x3d800000, v96
	v_cndmask_b32_e64 v161, v154, v97, s[6:7]
	s_waitcnt lgkmcnt(5)
	v_fmac_f32_e32 v155, 0x3d800000, v60
	v_cndmask_b32_e64 v162, v155, v61, s[6:7]
	s_waitcnt lgkmcnt(4)
	v_fmac_f32_e32 v156, 0x3d800000, v58
	v_cndmask_b32_e64 v163, v156, v59, s[6:7]
	s_waitcnt lgkmcnt(3)
	v_fmac_f32_e32 v157, 0x3d800000, v56
	v_cndmask_b32_e64 v164, v157, v57, s[6:7]
	s_waitcnt lgkmcnt(2)
	v_fmac_f32_e32 v158, 0x3d800000, v126
	v_cndmask_b32_e64 v165, v158, v127, s[6:7]
	s_waitcnt lgkmcnt(1)
	v_fmac_f32_e32 v159, 0x3d800000, v124
	v_cndmask_b32_e64 v166, v159, v125, s[6:7]
	s_waitcnt lgkmcnt(0)
	v_fmac_f32_e32 v160, 0x3d800000, v122
	v_cndmask_b32_e64 v167, v160, v123, s[6:7]
	ds_bpermute_b32 v154, v90, v161
	ds_bpermute_b32 v155, v90, v162
	ds_bpermute_b32 v156, v90, v163
	ds_bpermute_b32 v157, v90, v164
	ds_bpermute_b32 v158, v90, v165
	ds_bpermute_b32 v159, v90, v166
	ds_bpermute_b32 v160, v90, v167
	s_waitcnt lgkmcnt(6)
	v_add_f32_e32 v154, v161, v154
	v_cndmask_b32_e64 v161, v154, v161, s[8:9]
	s_waitcnt lgkmcnt(5)
	v_add_f32_e32 v155, v162, v155
	v_cndmask_b32_e64 v162, v155, v162, s[8:9]
	s_waitcnt lgkmcnt(4)
	v_add_f32_e32 v156, v163, v156
	v_cndmask_b32_e64 v163, v156, v163, s[8:9]
	s_waitcnt lgkmcnt(3)
	v_add_f32_e32 v157, v164, v157
	v_cndmask_b32_e64 v164, v157, v164, s[8:9]
	s_waitcnt lgkmcnt(2)
	v_add_f32_e32 v158, v165, v158
	v_cndmask_b32_e64 v165, v158, v165, s[8:9]
	s_waitcnt lgkmcnt(1)
	v_add_f32_e32 v159, v166, v159
	v_cndmask_b32_e64 v166, v159, v166, s[8:9]
	s_waitcnt lgkmcnt(0)
	v_add_f32_e32 v160, v167, v160
	v_cndmask_b32_e64 v167, v160, v167, s[8:9]
	ds_bpermute_b32 v154, v94, v161
	ds_bpermute_b32 v155, v94, v162
	ds_bpermute_b32 v156, v94, v163
	ds_bpermute_b32 v157, v94, v164
	ds_bpermute_b32 v158, v94, v165
	ds_bpermute_b32 v159, v94, v166
	ds_bpermute_b32 v160, v94, v167
	s_waitcnt lgkmcnt(6)
	v_add_f32_e32 v154, v161, v154
	v_cndmask_b32_e64 v161, v154, v161, s[10:11]
	s_waitcnt lgkmcnt(5)
	v_add_f32_e32 v155, v162, v155
	v_cndmask_b32_e64 v162, v155, v162, s[10:11]
	s_waitcnt lgkmcnt(4)
	v_add_f32_e32 v156, v163, v156
	v_cndmask_b32_e64 v163, v156, v163, s[10:11]
	s_waitcnt lgkmcnt(3)
	v_add_f32_e32 v157, v164, v157
	v_cndmask_b32_e64 v164, v157, v164, s[10:11]
	s_waitcnt lgkmcnt(2)
	v_add_f32_e32 v158, v165, v158
	v_cndmask_b32_e64 v165, v158, v165, s[10:11]
	s_waitcnt lgkmcnt(1)
	v_add_f32_e32 v159, v166, v159
	v_cndmask_b32_e64 v166, v159, v166, s[10:11]
	s_waitcnt lgkmcnt(0)
	v_add_f32_e32 v160, v167, v160
	v_cndmask_b32_e64 v167, v160, v167, s[10:11]
	ds_bpermute_b32 v154, v101, v161
	ds_bpermute_b32 v155, v101, v162
	ds_bpermute_b32 v156, v101, v163
	ds_bpermute_b32 v157, v101, v164
	ds_bpermute_b32 v158, v101, v165
	ds_bpermute_b32 v159, v101, v166
	ds_bpermute_b32 v160, v101, v167
	s_waitcnt lgkmcnt(6)
	v_add_f32_e32 v154, v161, v154
	v_cndmask_b32_e64 v161, v154, v161, s[12:13]
	s_waitcnt lgkmcnt(5)
	v_add_f32_e32 v155, v162, v155
	v_cndmask_b32_e64 v162, v155, v162, s[12:13]
	s_waitcnt lgkmcnt(4)
	v_add_f32_e32 v156, v163, v156
	v_cndmask_b32_e64 v163, v156, v163, s[12:13]
	s_waitcnt lgkmcnt(3)
	v_add_f32_e32 v157, v164, v157
	v_cndmask_b32_e64 v164, v157, v164, s[12:13]
	s_waitcnt lgkmcnt(2)
	v_add_f32_e32 v158, v165, v158
	v_cndmask_b32_e64 v165, v158, v165, s[12:13]
	s_waitcnt lgkmcnt(1)
	v_add_f32_e32 v159, v166, v159
	v_cndmask_b32_e64 v166, v159, v166, s[12:13]
	s_waitcnt lgkmcnt(0)
	v_add_f32_e32 v160, v167, v160
	v_cndmask_b32_e64 v167, v160, v167, s[12:13]
	ds_bpermute_b32 v154, v102, v161
	ds_bpermute_b32 v155, v102, v162
	ds_bpermute_b32 v156, v102, v163
	ds_bpermute_b32 v157, v102, v164
	ds_bpermute_b32 v158, v102, v165
	ds_bpermute_b32 v159, v102, v166
	ds_bpermute_b32 v160, v102, v167
	s_waitcnt lgkmcnt(6)
	v_add_f32_e32 v154, v161, v154
	v_cndmask_b32_e64 v161, v154, v161, s[14:15]
	s_waitcnt lgkmcnt(5)
	v_add_f32_e32 v155, v162, v155
	v_cndmask_b32_e64 v162, v155, v162, s[14:15]
	s_waitcnt lgkmcnt(4)
	v_add_f32_e32 v156, v163, v156
	v_cndmask_b32_e64 v163, v156, v163, s[14:15]
	s_waitcnt lgkmcnt(3)
	v_add_f32_e32 v157, v164, v157
	v_cndmask_b32_e64 v164, v157, v164, s[14:15]
	s_waitcnt lgkmcnt(2)
	v_add_f32_e32 v158, v165, v158
	v_cndmask_b32_e64 v165, v158, v165, s[14:15]
	s_waitcnt lgkmcnt(1)
	v_add_f32_e32 v159, v166, v159
	v_cndmask_b32_e64 v166, v159, v166, s[14:15]
	s_waitcnt lgkmcnt(0)
	v_add_f32_e32 v160, v167, v160
	v_cndmask_b32_e64 v167, v160, v167, s[14:15]
	ds_bpermute_b32 v154, v92, v161
	ds_bpermute_b32 v155, v92, v162
	ds_bpermute_b32 v156, v92, v163
	ds_bpermute_b32 v157, v92, v164
	ds_bpermute_b32 v158, v92, v165
	ds_bpermute_b32 v159, v92, v166
	ds_bpermute_b32 v160, v92, v167
	s_waitcnt lgkmcnt(6)
	v_add_f32_e32 v68, v161, v154
	v_cndmask_b32_e64 v106, v68, v161, s[4:5]
	s_waitcnt lgkmcnt(5)
	v_add_f32_e32 v60, v162, v155
	v_cndmask_b32_e64 v108, v60, v162, s[4:5]
	s_waitcnt lgkmcnt(4)
	v_add_f32_e32 v58, v163, v156
	v_cndmask_b32_e64 v110, v58, v163, s[4:5]
	s_waitcnt lgkmcnt(3)
	v_add_f32_e32 v56, v164, v157
	v_cndmask_b32_e64 v111, v56, v164, s[4:5]
	s_waitcnt lgkmcnt(2)
	v_add_f32_e32 v57, v165, v158
	v_cndmask_b32_e64 v126, v57, v165, s[4:5]
	s_waitcnt lgkmcnt(1)
	v_add_f32_e32 v59, v166, v159
	v_cndmask_b32_e64 v124, v59, v166, s[4:5]
	s_waitcnt lgkmcnt(0)
; __device__ __forceinline__ void gla_gates(const bf16* prow, const float* wg, const float* bg, int h, int lane, float (&bc)[32], LAS float* Wst) {
;     ...
;     for (int d = 0; d < 32; ++d) { float v = bc[d];
; #pragma unroll
;         for (int off = 1; off < 64; off <<= 1) { const float t = __shfl_up(v, off); if (lane >= off) v += t; }
;         bc[d] = v; }
	v_add_f32_e32 v61, v167, v160
	v_cndmask_b32_e64 v122, v61, v167, s[4:5]
	ds_bpermute_b32 v154, v88, v121
	ds_bpermute_b32 v155, v88, v119
	ds_bpermute_b32 v156, v88, v117
	ds_bpermute_b32 v157, v88, v115
	ds_bpermute_b32 v158, v88, v113
	s_waitcnt lgkmcnt(4)
	v_fmac_f32_e32 v154, 0x3d800000, v120
	v_cndmask_b32_e64 v161, v154, v121, s[6:7]
	s_waitcnt lgkmcnt(3)
	v_fmac_f32_e32 v155, 0x3d800000, v118
	v_cndmask_b32_e64 v162, v155, v119, s[6:7]
	s_waitcnt lgkmcnt(2)
	v_fmac_f32_e32 v156, 0x3d800000, v116
	v_cndmask_b32_e64 v163, v156, v117, s[6:7]
	s_waitcnt lgkmcnt(1)
	v_fmac_f32_e32 v157, 0x3d800000, v114
	v_cndmask_b32_e64 v164, v157, v115, s[6:7]
	s_waitcnt lgkmcnt(0)
	v_fmac_f32_e32 v158, 0x3d800000, v112
	v_cndmask_b32_e64 v165, v158, v113, s[6:7]
	ds_bpermute_b32 v154, v90, v161
	ds_bpermute_b32 v155, v90, v162
	ds_bpermute_b32 v156, v90, v163
	ds_bpermute_b32 v157, v90, v164
	ds_bpermute_b32 v158, v90, v165
	s_waitcnt lgkmcnt(4)
	v_add_f32_e32 v154, v161, v154
	v_cndmask_b32_e64 v161, v154, v161, s[8:9]
	s_waitcnt lgkmcnt(3)
	v_add_f32_e32 v155, v162, v155
	v_cndmask_b32_e64 v162, v155, v162, s[8:9]
	s_waitcnt lgkmcnt(2)
	v_add_f32_e32 v156, v163, v156
	v_cndmask_b32_e64 v163, v156, v163, s[8:9]
	s_waitcnt lgkmcnt(1)
	v_add_f32_e32 v157, v164, v157
	v_cndmask_b32_e64 v164, v157, v164, s[8:9]
	s_waitcnt lgkmcnt(0)
	v_add_f32_e32 v158, v165, v158
	v_cndmask_b32_e64 v165, v158, v165, s[8:9]
	ds_bpermute_b32 v154, v94, v161
	ds_bpermute_b32 v155, v94, v162
	ds_bpermute_b32 v156, v94, v163
	ds_bpermute_b32 v157, v94, v164
	ds_bpermute_b32 v158, v94, v165
	s_waitcnt lgkmcnt(4)
	v_add_f32_e32 v154, v161, v154
	v_cndmask_b32_e64 v161, v154, v161, s[10:11]
	s_waitcnt lgkmcnt(3)
	v_add_f32_e32 v155, v162, v155
	v_cndmask_b32_e64 v162, v155, v162, s[10:11]
	s_waitcnt lgkmcnt(2)
	v_add_f32_e32 v156, v163, v156
	v_cndmask_b32_e64 v163, v156, v163, s[10:11]
	s_waitcnt lgkmcnt(1)
	v_add_f32_e32 v157, v164, v157
	v_cndmask_b32_e64 v164, v157, v164, s[10:11]
	s_waitcnt lgkmcnt(0)
	v_add_f32_e32 v158, v165, v158
	v_cndmask_b32_e64 v165, v158, v165, s[10:11]
	ds_bpermute_b32 v154, v101, v161
	ds_bpermute_b32 v155, v101, v162
	ds_bpermute_b32 v156, v101, v163
	ds_bpermute_b32 v157, v101, v164
	ds_bpermute_b32 v158, v101, v165
	s_waitcnt lgkmcnt(4)
	v_add_f32_e32 v154, v161, v154
	v_cndmask_b32_e64 v161, v154, v161, s[12:13]
	s_waitcnt lgkmcnt(3)
	v_add_f32_e32 v155, v162, v155
	v_cndmask_b32_e64 v162, v155, v162, s[12:13]
	s_waitcnt lgkmcnt(2)
	v_add_f32_e32 v156, v163, v156
	v_cndmask_b32_e64 v163, v156, v163, s[12:13]
	s_waitcnt lgkmcnt(1)
	v_add_f32_e32 v157, v164, v157
	v_cndmask_b32_e64 v164, v157, v164, s[12:13]
	s_waitcnt lgkmcnt(0)
	v_add_f32_e32 v158, v165, v158
	v_cndmask_b32_e64 v165, v158, v165, s[12:13]
	ds_bpermute_b32 v154, v102, v161
	ds_bpermute_b32 v155, v102, v162
	ds_bpermute_b32 v156, v102, v163
	ds_bpermute_b32 v157, v102, v164
	ds_bpermute_b32 v158, v102, v165
	s_waitcnt lgkmcnt(4)
	v_add_f32_e32 v154, v161, v154
	v_cndmask_b32_e64 v161, v154, v161, s[14:15]
	s_waitcnt lgkmcnt(3)
	v_add_f32_e32 v155, v162, v155
	v_cndmask_b32_e64 v162, v155, v162, s[14:15]
	s_waitcnt lgkmcnt(2)
	v_add_f32_e32 v156, v163, v156
	v_cndmask_b32_e64 v163, v156, v163, s[14:15]
	s_waitcnt lgkmcnt(1)
	v_add_f32_e32 v157, v164, v157
	v_cndmask_b32_e64 v164, v157, v164, s[14:15]
	s_waitcnt lgkmcnt(0)
	v_add_f32_e32 v158, v165, v158
	v_cndmask_b32_e64 v165, v158, v165, s[14:15]
	ds_bpermute_b32 v154, v92, v161
	ds_bpermute_b32 v155, v92, v162
	ds_bpermute_b32 v156, v92, v163
	ds_bpermute_b32 v157, v92, v164
	ds_bpermute_b32 v158, v92, v165
	s_waitcnt lgkmcnt(4)
	v_add_f32_e32 v86, v161, v154
	v_cndmask_b32_e64 v120, v86, v161, s[4:5]
	s_waitcnt lgkmcnt(3)
	v_add_f32_e32 v91, v162, v155
	v_cndmask_b32_e64 v118, v91, v162, s[4:5]
	s_waitcnt lgkmcnt(2)
	v_add_f32_e32 v96, v163, v156
	v_cndmask_b32_e64 v116, v96, v163, s[4:5]
	s_waitcnt lgkmcnt(1)
	v_add_f32_e32 v97, v164, v157
	v_cndmask_b32_e64 v119, v97, v164, s[4:5]
	s_waitcnt lgkmcnt(0)
	v_add_f32_e32 v104, v165, v158
	v_cndmask_b32_e64 v121, v104, v165, s[4:5]
	ds_bpermute_b32 v107, v88, v143
	s_waitcnt lgkmcnt(0)
	v_fmac_f32_e32 v107, 0x3d800000, v142
	v_cndmask_b32_e64 v107, v107, v143, s[6:7]
	ds_bpermute_b32 v109, v90, v107
	v_and_b32_e32 v142, 0xffff0000, v42
	v_lshlrev_b32_e32 v143, 16, v43
	s_waitcnt lgkmcnt(0)
	v_add_f32_e32 v109, v107, v109
	v_cndmask_b32_e64 v107, v109, v107, s[8:9]
	ds_bpermute_b32 v109, v94, v107
	s_waitcnt lgkmcnt(0)
	v_add_f32_e32 v109, v107, v109
	v_cndmask_b32_e64 v107, v109, v107, s[10:11]
	ds_bpermute_b32 v109, v101, v107
	s_waitcnt lgkmcnt(0)
	v_add_f32_e32 v109, v107, v109
	v_cndmask_b32_e64 v107, v109, v107, s[12:13]
	ds_bpermute_b32 v109, v102, v107
	s_waitcnt lgkmcnt(0)
	v_add_f32_e32 v109, v107, v109
	v_cndmask_b32_e64 v109, v109, v107, s[14:15]
	ds_bpermute_b32 v107, v92, v109
	s_waitcnt lgkmcnt(0)
	v_add_f32_e32 v107, v109, v107
	v_cndmask_b32_e64 v125, v107, v109, s[4:5]
	ds_bpermute_b32 v109, v88, v141
	s_waitcnt lgkmcnt(0)
	v_fmac_f32_e32 v109, 0x3d800000, v140
	v_cndmask_b32_e64 v109, v109, v141, s[6:7]
	ds_bpermute_b32 v112, v90, v109
	v_lshlrev_b32_e32 v141, 16, v42
	v_lshlrev_b32_e32 v42, 16, v34
	v_and_b32_e32 v140, 0xffff0000, v49
	s_waitcnt lgkmcnt(0)
	v_add_f32_e32 v112, v109, v112
	v_cndmask_b32_e64 v109, v112, v109, s[8:9]
	ds_bpermute_b32 v112, v94, v109
	s_waitcnt lgkmcnt(0)
	v_add_f32_e32 v112, v109, v112
	v_cndmask_b32_e64 v109, v112, v109, s[10:11]
	ds_bpermute_b32 v112, v101, v109
	s_waitcnt lgkmcnt(0)
	v_add_f32_e32 v112, v109, v112
	v_cndmask_b32_e64 v109, v112, v109, s[12:13]
	ds_bpermute_b32 v112, v102, v109
	s_waitcnt lgkmcnt(0)
; __device__ __forceinline__ void gla_gates(const bf16* prow, const float* wg, const float* bg, int h, int lane, float (&bc)[32], LAS float* Wst) {
;     ...
;     for (int d = 0; d < 32; ++d) { float v = bc[d];
; #pragma unroll
;         for (int off = 1; off < 64; off <<= 1) { const float t = __shfl_up(v, off); if (lane >= off) v += t; }
;         bc[d] = v; }
	v_add_f32_e32 v112, v109, v112
	v_cndmask_b32_e64 v112, v112, v109, s[14:15]
	ds_bpermute_b32 v109, v92, v112
	s_waitcnt lgkmcnt(0)
	v_add_f32_e32 v109, v112, v109
	v_cndmask_b32_e64 v127, v109, v112, s[4:5]
	ds_bpermute_b32 v112, v88, v139
	s_waitcnt lgkmcnt(0)
	v_fmac_f32_e32 v112, 0x3d800000, v138
	v_cndmask_b32_e64 v112, v112, v139, s[6:7]
	ds_bpermute_b32 v113, v90, v112
	v_lshlrev_b32_e32 v139, 16, v49
	v_and_b32_e32 v49, 0xffff0000, v38
	s_waitcnt lgkmcnt(0)
	v_add_f32_e32 v113, v112, v113
	v_cndmask_b32_e64 v112, v113, v112, s[8:9]
	ds_bpermute_b32 v113, v94, v112
	s_waitcnt lgkmcnt(0)
	v_add_f32_e32 v113, v112, v113
	v_cndmask_b32_e64 v112, v113, v112, s[10:11]
	ds_bpermute_b32 v113, v101, v112
	s_waitcnt lgkmcnt(0)
	v_add_f32_e32 v113, v112, v113
	v_cndmask_b32_e64 v112, v113, v112, s[12:13]
	ds_bpermute_b32 v113, v102, v112
	s_waitcnt lgkmcnt(0)
	v_add_f32_e32 v113, v112, v113
	v_cndmask_b32_e64 v113, v113, v112, s[14:15]
	ds_bpermute_b32 v112, v92, v113
	s_waitcnt lgkmcnt(0)
	v_add_f32_e32 v112, v113, v112
	v_cndmask_b32_e64 v138, v112, v113, s[4:5]
	ds_bpermute_b32 v113, v88, v137
	s_waitcnt lgkmcnt(0)
	v_fmac_f32_e32 v113, 0x3d800000, v136
	v_cndmask_b32_e64 v113, v113, v137, s[6:7]
	ds_bpermute_b32 v114, v90, v113
	v_and_b32_e32 v137, 0xffff0000, v48
	s_waitcnt lgkmcnt(0)
	v_add_f32_e32 v114, v113, v114
	v_cndmask_b32_e64 v113, v114, v113, s[8:9]
	ds_bpermute_b32 v114, v94, v113
	s_waitcnt lgkmcnt(0)
	v_add_f32_e32 v114, v113, v114
	v_cndmask_b32_e64 v113, v114, v113, s[10:11]
	ds_bpermute_b32 v114, v101, v113
	s_waitcnt lgkmcnt(0)
	v_add_f32_e32 v114, v113, v114
	v_cndmask_b32_e64 v113, v114, v113, s[12:13]
	ds_bpermute_b32 v114, v102, v113
	s_waitcnt lgkmcnt(0)
	v_add_f32_e32 v114, v113, v114
	v_cndmask_b32_e64 v114, v114, v113, s[14:15]
	ds_bpermute_b32 v113, v92, v114
	s_waitcnt lgkmcnt(0)
	v_add_f32_e32 v113, v114, v113
	v_cndmask_b32_e64 v136, v113, v114, s[4:5]
	ds_bpermute_b32 v114, v88, v135
	s_waitcnt lgkmcnt(0)
	v_fmac_f32_e32 v114, 0x3d800000, v134
	v_cndmask_b32_e64 v114, v114, v135, s[6:7]
	ds_bpermute_b32 v115, v90, v114
	v_lshlrev_b32_e32 v135, 16, v48
	v_lshlrev_b32_e32 v48, 16, v39
	s_waitcnt lgkmcnt(0)
	v_add_f32_e32 v115, v114, v115
	v_cndmask_b32_e64 v114, v115, v114, s[8:9]
	ds_bpermute_b32 v115, v94, v114
	s_waitcnt lgkmcnt(0)
	v_add_f32_e32 v115, v114, v115
	v_cndmask_b32_e64 v114, v115, v114, s[10:11]
	ds_bpermute_b32 v115, v101, v114
	s_waitcnt lgkmcnt(0)
	v_add_f32_e32 v115, v114, v115
	v_cndmask_b32_e64 v114, v115, v114, s[12:13]
	ds_bpermute_b32 v115, v102, v114
	s_waitcnt lgkmcnt(0)
	v_add_f32_e32 v115, v114, v115
	v_cndmask_b32_e64 v115, v115, v114, s[14:15]
	ds_bpermute_b32 v114, v92, v115
	s_waitcnt lgkmcnt(0)
	v_add_f32_e32 v114, v115, v114
	v_cndmask_b32_e64 v134, v114, v115, s[4:5]
	ds_bpermute_b32 v115, v88, v133
	s_waitcnt lgkmcnt(0)
	v_fmac_f32_e32 v115, 0x3d800000, v132
	v_cndmask_b32_e64 v115, v115, v133, s[6:7]
	ds_bpermute_b32 v117, v90, v115
	v_and_b32_e32 v133, 0xffff0000, v47
	s_waitcnt lgkmcnt(0)
	v_add_f32_e32 v117, v115, v117
	v_cndmask_b32_e64 v115, v117, v115, s[8:9]
	ds_bpermute_b32 v117, v94, v115
	s_waitcnt lgkmcnt(0)
	v_add_f32_e32 v117, v115, v117
	v_cndmask_b32_e64 v115, v117, v115, s[10:11]
	ds_bpermute_b32 v117, v101, v115
	s_waitcnt lgkmcnt(0)
	v_add_f32_e32 v117, v115, v117
	v_cndmask_b32_e64 v115, v117, v115, s[12:13]
	ds_bpermute_b32 v117, v102, v115
	s_waitcnt lgkmcnt(0)
	v_add_f32_e32 v117, v115, v117
	v_cndmask_b32_e64 v117, v117, v115, s[14:15]
	ds_bpermute_b32 v115, v92, v117
	s_waitcnt lgkmcnt(0)
	v_add_f32_e32 v115, v117, v115
	v_cndmask_b32_e64 v132, v115, v117, s[4:5]
	ds_bpermute_b32 v117, v88, v131
	s_waitcnt lgkmcnt(0)
	v_fmac_f32_e32 v117, 0x3d800000, v130
	v_cndmask_b32_e64 v117, v117, v131, s[6:7]
	ds_bpermute_b32 v123, v90, v117
	ds_bpermute_b32 v131, v88, v84
	s_waitcnt lgkmcnt(1)
	v_add_f32_e32 v123, v117, v123
	v_cndmask_b32_e64 v117, v123, v117, s[8:9]
	ds_bpermute_b32 v123, v94, v117
	s_waitcnt lgkmcnt(1)
	v_fmac_f32_e32 v131, 0x3d800000, v82
	v_cndmask_b32_e64 v82, v131, v84, s[6:7]
	ds_bpermute_b32 v131, v88, v78
	ds_bpermute_b32 v84, v90, v82
	s_waitcnt lgkmcnt(2)
	v_add_f32_e32 v123, v117, v123
	v_cndmask_b32_e64 v117, v123, v117, s[10:11]
	ds_bpermute_b32 v123, v101, v117
	s_waitcnt lgkmcnt(2)
	v_fmac_f32_e32 v131, 0x3d800000, v76
	v_cndmask_b32_e64 v76, v131, v78, s[6:7]
	ds_bpermute_b32 v78, v90, v76
	s_waitcnt lgkmcnt(2)
	v_add_f32_e32 v84, v82, v84
	s_waitcnt lgkmcnt(1)
	v_add_f32_e32 v123, v117, v123
	v_cndmask_b32_e64 v117, v123, v117, s[12:13]
	ds_bpermute_b32 v123, v102, v117
	s_waitcnt lgkmcnt(1)
	v_add_f32_e32 v78, v76, v78
	v_cndmask_b32_e64 v82, v84, v82, s[8:9]
	v_cndmask_b32_e64 v76, v78, v76, s[8:9]
	ds_bpermute_b32 v84, v94, v82
	s_waitcnt lgkmcnt(1)
	v_add_f32_e32 v123, v117, v123
	v_cndmask_b32_e64 v123, v123, v117, s[14:15]
	ds_bpermute_b32 v117, v92, v123
	ds_bpermute_b32 v78, v94, v76
	s_waitcnt lgkmcnt(2)
	v_add_f32_e32 v84, v82, v84
	v_cndmask_b32_e64 v82, v84, v82, s[10:11]
	ds_bpermute_b32 v84, v101, v82
	s_waitcnt lgkmcnt(2)
	v_add_f32_e32 v117, v123, v117
	v_cndmask_b32_e64 v130, v117, v123, s[4:5]
	ds_bpermute_b32 v123, v88, v129
	s_waitcnt lgkmcnt(2)
	v_add_f32_e32 v78, v76, v78
	v_cndmask_b32_e64 v76, v78, v76, s[10:11]
	ds_bpermute_b32 v78, v101, v76
	s_waitcnt lgkmcnt(2)
	v_add_f32_e32 v84, v82, v84
	s_waitcnt lgkmcnt(1)
	v_fmac_f32_e32 v123, 0x3d800000, v128
	v_cndmask_b32_e64 v123, v123, v129, s[6:7]
	ds_bpermute_b32 v129, v88, v144
	ds_bpermute_b32 v88, v88, v72
	ds_bpermute_b32 v128, v90, v123
	s_waitcnt lgkmcnt(3)
	v_add_f32_e32 v78, v76, v78
	v_cndmask_b32_e64 v82, v84, v82, s[12:13]
	s_waitcnt lgkmcnt(2)
; __device__ __forceinline__ unsigned pk2(float lo, float hi) { const f32x2_ v = {lo, hi}; return __builtin_bit_cast(unsigned, __builtin_convertvector(v, bf16x2_)); }
; __device__ __forceinline__ void gla_gates(const bf16* prow, const float* wg, const float* bg, int h, int lane, float (&bc)[32], LAS float* Wst) {
;     ...
;     for (int d = 0; d < 32; ++d) { float v = bc[d];
; #pragma unroll
;         for (int off = 1; off < 64; off <<= 1) { const float t = __shfl_up(v, off); if (lane >= off) v += t; }
;         bc[d] = v; }
; __device__ __forceinline__ void gla_local_unit(int u, const bf16* proj, const float* wg, const float* bg, float* KV, float* DEC, LAS unsigned char* wl, int lane) {
;     ...
; #pragma unroll
;       for (int d = 0; d < 32; ++d) { const float bl = __shfl(bc[d], 63); KstT[d * 68 + lane] = (bf16)(pk2(k[d] * __expf(bl - bc[d]), 0.f) & 0xffffu); } }
	v_fmac_f32_e32 v129, 0x3d800000, v103
	s_waitcnt lgkmcnt(1)
	v_fmac_f32_e32 v88, 0x3d800000, v70
	v_cndmask_b32_e64 v103, v129, v144, s[6:7]
	v_cndmask_b32_e64 v70, v88, v72, s[6:7]
	ds_bpermute_b32 v129, v90, v103
	ds_bpermute_b32 v72, v90, v70
	s_waitcnt lgkmcnt(2)
	v_add_f32_e32 v128, v123, v128
	v_cndmask_b32_e64 v123, v128, v123, s[8:9]
	ds_bpermute_b32 v128, v94, v123
	s_waitcnt lgkmcnt(2)
	v_add_f32_e32 v129, v103, v129
	s_waitcnt lgkmcnt(1)
	v_add_f32_e32 v72, v70, v72
	v_cndmask_b32_e64 v103, v129, v103, s[8:9]
	v_cndmask_b32_e64 v70, v72, v70, s[8:9]
	ds_bpermute_b32 v129, v94, v103
	ds_bpermute_b32 v72, v94, v70
	s_waitcnt lgkmcnt(2)
	v_add_f32_e32 v128, v123, v128
	v_cndmask_b32_e64 v123, v128, v123, s[10:11]
	ds_bpermute_b32 v128, v101, v123
	s_waitcnt lgkmcnt(2)
	v_add_f32_e32 v129, v103, v129
	s_waitcnt lgkmcnt(1)
	v_add_f32_e32 v72, v70, v72
	v_cndmask_b32_e64 v103, v129, v103, s[10:11]
	v_cndmask_b32_e64 v70, v72, v70, s[10:11]
	ds_bpermute_b32 v129, v101, v103
	ds_bpermute_b32 v72, v101, v70
	s_waitcnt lgkmcnt(2)
	v_add_f32_e32 v128, v123, v128
	v_cndmask_b32_e64 v123, v128, v123, s[12:13]
	v_cndmask_b32_e64 v76, v78, v76, s[12:13]
	s_waitcnt lgkmcnt(1)
	v_add_f32_e32 v129, v103, v129
	s_waitcnt lgkmcnt(0)
	v_add_f32_e32 v72, v70, v72
	v_cndmask_b32_e64 v103, v129, v103, s[12:13]
	v_cndmask_b32_e64 v70, v72, v70, s[12:13]
	ds_bpermute_b32 v128, v102, v123
	ds_bpermute_b32 v129, v102, v103
	ds_bpermute_b32 v84, v102, v82
	ds_bpermute_b32 v78, v102, v76
	ds_bpermute_b32 v72, v102, v70
	s_waitcnt lgkmcnt(4)
	v_add_f32_e32 v128, v123, v128
	s_waitcnt lgkmcnt(3)
	v_add_f32_e32 v129, v103, v129
	s_waitcnt lgkmcnt(2)
	v_add_f32_e32 v84, v82, v84
	s_waitcnt lgkmcnt(1)
	v_add_f32_e32 v78, v76, v78
	s_waitcnt lgkmcnt(0)
	v_add_f32_e32 v72, v70, v72
	v_cndmask_b32_e64 v128, v128, v123, s[14:15]
	v_cndmask_b32_e64 v129, v129, v103, s[14:15]
	v_cndmask_b32_e64 v84, v84, v82, s[14:15]
	v_cndmask_b32_e64 v78, v78, v76, s[14:15]
	v_cndmask_b32_e64 v72, v72, v70, s[14:15]
	ds_bpermute_b32 v123, v92, v128
	ds_bpermute_b32 v103, v92, v129
	ds_bpermute_b32 v82, v92, v84
	ds_bpermute_b32 v76, v92, v78
	ds_bpermute_b32 v70, v92, v72
	v_lshlrev_b32_e32 v101, 16, v46
	v_and_b32_e32 v102, 0xffff0000, v46
	v_lshlrev_b32_e32 v131, 16, v47
	v_and_b32_e32 v144, 0xffff0000, v43
	v_and_b32_e32 v94, 0xffff0000, v44
	v_lshlrev_b32_e32 v92, 16, v45
	v_and_b32_e32 v90, 0xffff0000, v45
	v_and_b32_e32 v47, 0xffff0000, v39
	v_lshlrev_b32_e32 v46, 16, v40
	v_and_b32_e32 v45, 0xffff0000, v40
	v_lshlrev_b32_e32 v44, 16, v41
	v_and_b32_e32 v43, 0xffff0000, v41
	v_and_b32_e32 v41, 0xffff0000, v34
	v_lshlrev_b32_e32 v40, 16, v35
	v_and_b32_e32 v39, 0xffff0000, v35
	v_lshlrev_b32_e32 v35, 16, v37
	v_and_b32_e32 v34, 0xffff0000, v37
	ds_bpermute_b32 v37, v242, v74
	v_lshlrev_b32_e32 v88, 16, v38
	s_waitcnt lgkmcnt(5)
	v_add_f32_e32 v123, v128, v123
	v_cndmask_b32_e64 v128, v123, v128, s[4:5]
	s_waitcnt lgkmcnt(4)
	v_add_f32_e32 v103, v129, v103
	s_waitcnt lgkmcnt(0)
	v_sub_f32_e32 v37, v37, v74
	v_mul_f32_e32 v37, 0x3fb8aa3b, v37
	v_exp_f32_e32 v37, v37
	v_cndmask_b32_e64 v129, v103, v129, s[4:5]
	v_lshlrev_b32_e32 v38, 16, v36
	v_add_f32_e32 v82, v84, v82
	v_mul_f32_e32 v37, v37, v101
	v_cvt_pk_bf16_f32 v37, v37, s0
	ds_write_b16 v85, v37
	ds_bpermute_b32 v37, v242, v80
	v_cndmask_b32_e64 v84, v82, v84, s[4:5]
	v_and_b32_e32 v36, 0xffff0000, v36
	v_add_f32_e32 v76, v78, v76
	v_cndmask_b32_e64 v78, v76, v78, s[4:5]
	s_waitcnt lgkmcnt(0)
	v_sub_f32_e32 v37, v37, v80
	v_mul_f32_e32 v37, 0x3fb8aa3b, v37
	v_exp_f32_e32 v37, v37
	v_add_f32_e32 v70, v72, v70
	v_cndmask_b32_e64 v72, v70, v72, s[4:5]
	v_mul_f32_e32 v37, v37, v102
	v_cvt_pk_bf16_f32 v37, v37, s0
	ds_write_b16 v85, v37 offset:136
	ds_bpermute_b32 v37, v242, v95
	s_waitcnt lgkmcnt(0)
	v_sub_f32_e32 v37, v37, v95
	v_mul_f32_e32 v37, 0x3fb8aa3b, v37
	v_exp_f32_e32 v37, v37
	s_nop 0
	v_mul_f32_e32 v37, v37, v131
	v_cvt_pk_bf16_f32 v37, v37, s0
	ds_write_b16 v85, v37 offset:272
	ds_bpermute_b32 v37, v242, v93
	s_waitcnt lgkmcnt(0)
	v_sub_f32_e32 v37, v37, v93
	v_mul_f32_e32 v37, 0x3fb8aa3b, v37
	v_exp_f32_e32 v37, v37
	s_nop 0
	v_mul_f32_e32 v37, v37, v133
	v_cvt_pk_bf16_f32 v37, v37, s0
	ds_write_b16 v85, v37 offset:408
	ds_bpermute_b32 v37, v242, v98
	s_waitcnt lgkmcnt(0)
	v_sub_f32_e32 v37, v37, v98
	v_mul_f32_e32 v37, 0x3fb8aa3b, v37
	v_exp_f32_e32 v37, v37
	s_nop 0
	v_mul_f32_e32 v37, v37, v135
	v_cvt_pk_bf16_f32 v37, v37, s0
	ds_write_b16 v85, v37 offset:544
	ds_bpermute_b32 v37, v242, v99
	s_waitcnt lgkmcnt(0)
	v_sub_f32_e32 v37, v37, v99
	v_mul_f32_e32 v37, 0x3fb8aa3b, v37
	v_exp_f32_e32 v37, v37
	s_nop 0
	v_mul_f32_e32 v37, v37, v137
	v_cvt_pk_bf16_f32 v37, v37, s0
	ds_write_b16 v85, v37 offset:680
	ds_bpermute_b32 v37, v242, v100
	s_waitcnt lgkmcnt(0)
	v_sub_f32_e32 v37, v37, v100
	v_mul_f32_e32 v37, 0x3fb8aa3b, v37
	v_exp_f32_e32 v37, v37
	s_nop 0
	v_mul_f32_e32 v37, v37, v139
	v_cvt_pk_bf16_f32 v37, v37, s0
	ds_write_b16 v85, v37 offset:816
	ds_bpermute_b32 v37, v242, v105
	s_waitcnt lgkmcnt(0)
	v_sub_f32_e32 v37, v37, v105
	v_mul_f32_e32 v37, 0x3fb8aa3b, v37
	v_exp_f32_e32 v37, v37
	s_nop 0
	v_mul_f32_e32 v37, v37, v140
	v_cvt_pk_bf16_f32 v37, v37, s0
	ds_write_b16 v85, v37 offset:952
	ds_bpermute_b32 v37, v242, v106
	s_waitcnt lgkmcnt(0)
	v_sub_f32_e32 v37, v37, v106
	v_mul_f32_e32 v37, 0x3fb8aa3b, v37
	v_exp_f32_e32 v37, v37
	s_nop 0
	v_mul_f32_e32 v37, v37, v141
	v_cvt_pk_bf16_f32 v37, v37, s0
	ds_write_b16 v85, v37 offset:1088
	ds_bpermute_b32 v37, v242, v108
	s_waitcnt lgkmcnt(0)
; __device__ __forceinline__ unsigned pk2(float lo, float hi) { const f32x2_ v = {lo, hi}; return __builtin_bit_cast(unsigned, __builtin_convertvector(v, bf16x2_)); }
; __device__ __forceinline__ void gla_local_unit(int u, const bf16* proj, const float* wg, const float* bg, float* KV, float* DEC, LAS unsigned char* wl, int lane) {
;     ...
; #pragma unroll
;       for (int d = 0; d < 32; ++d) { const float bl = __shfl(bc[d], 63); KstT[d * 68 + lane] = (bf16)(pk2(k[d] * __expf(bl - bc[d]), 0.f) & 0xffffu); } }
	v_sub_f32_e32 v37, v37, v108
	v_mul_f32_e32 v37, 0x3fb8aa3b, v37
	v_exp_f32_e32 v37, v37
	s_nop 0
	v_mul_f32_e32 v37, v37, v142
	v_cvt_pk_bf16_f32 v37, v37, s0
	ds_write_b16 v85, v37 offset:1224
	ds_bpermute_b32 v37, v242, v110
	s_waitcnt lgkmcnt(0)
	v_sub_f32_e32 v37, v37, v110
	v_mul_f32_e32 v37, 0x3fb8aa3b, v37
	v_exp_f32_e32 v37, v37
	s_nop 0
	v_mul_f32_e32 v37, v37, v143
	v_cvt_pk_bf16_f32 v37, v37, s0
	ds_write_b16 v85, v37 offset:1360
	ds_bpermute_b32 v37, v242, v111
	s_waitcnt lgkmcnt(0)
	v_sub_f32_e32 v37, v37, v111
	v_mul_f32_e32 v37, 0x3fb8aa3b, v37
	v_exp_f32_e32 v37, v37
	s_nop 0
	v_mul_f32_e32 v37, v37, v144
	v_cvt_pk_bf16_f32 v37, v37, s0
	ds_write_b16 v85, v37 offset:1496
	ds_bpermute_b32 v37, v242, v126
	s_waitcnt lgkmcnt(0)
	v_sub_f32_e32 v37, v37, v126
	v_mul_f32_e32 v37, 0x3fb8aa3b, v37
	v_exp_f32_e32 v37, v37
	s_nop 0
	v_mul_f32_e32 v37, v37, v145
	v_cvt_pk_bf16_f32 v37, v37, s0
	ds_write_b16 v85, v37 offset:1632
	ds_bpermute_b32 v37, v242, v124
	s_waitcnt lgkmcnt(0)
	v_sub_f32_e32 v37, v37, v124
	v_mul_f32_e32 v37, 0x3fb8aa3b, v37
	v_exp_f32_e32 v37, v37
	s_nop 0
	v_mul_f32_e32 v37, v37, v94
	v_cvt_pk_bf16_f32 v37, v37, s0
	ds_write_b16 v85, v37 offset:1768
	ds_bpermute_b32 v37, v242, v122
	s_waitcnt lgkmcnt(0)
	v_sub_f32_e32 v37, v37, v122
	v_mul_f32_e32 v37, 0x3fb8aa3b, v37
	v_exp_f32_e32 v37, v37
	s_nop 0
	v_mul_f32_e32 v37, v37, v92
	v_cvt_pk_bf16_f32 v37, v37, s0
	ds_write_b16 v85, v37 offset:1904
	ds_bpermute_b32 v37, v242, v120
	s_waitcnt lgkmcnt(0)
	v_sub_f32_e32 v37, v37, v120
	v_mul_f32_e32 v37, 0x3fb8aa3b, v37
	v_exp_f32_e32 v37, v37
	s_nop 0
	v_mul_f32_e32 v37, v37, v90
	v_cvt_pk_bf16_f32 v37, v37, s0
	ds_write_b16 v85, v37 offset:2040
	ds_bpermute_b32 v37, v242, v118
	s_waitcnt lgkmcnt(0)
	v_sub_f32_e32 v37, v37, v118
	v_mul_f32_e32 v37, 0x3fb8aa3b, v37
	v_exp_f32_e32 v37, v37
	s_nop 0
	v_mul_f32_e32 v37, v37, v88
	v_cvt_pk_bf16_f32 v37, v37, s0
	ds_write_b16 v85, v37 offset:2176
	ds_bpermute_b32 v37, v242, v116
	s_waitcnt lgkmcnt(0)
	v_sub_f32_e32 v37, v37, v116
	v_mul_f32_e32 v37, 0x3fb8aa3b, v37
	v_exp_f32_e32 v37, v37
	s_nop 0
	v_mul_f32_e32 v37, v37, v49
	v_cvt_pk_bf16_f32 v37, v37, s0
	ds_write_b16 v85, v37 offset:2312
	ds_bpermute_b32 v37, v242, v119
	s_waitcnt lgkmcnt(0)
	v_sub_f32_e32 v37, v37, v119
	v_mul_f32_e32 v37, 0x3fb8aa3b, v37
	v_exp_f32_e32 v37, v37
	s_nop 0
	v_mul_f32_e32 v37, v37, v48
	v_cvt_pk_bf16_f32 v37, v37, s0
	ds_write_b16 v85, v37 offset:2448
	ds_bpermute_b32 v37, v242, v121
	v_add_u32_e32 v48, 0x1000, v89
	s_waitcnt lgkmcnt(0)
	v_sub_f32_e32 v37, v37, v121
	v_mul_f32_e32 v37, 0x3fb8aa3b, v37
	v_exp_f32_e32 v37, v37
	s_nop 0
	v_mul_f32_e32 v37, v37, v47
	v_cvt_pk_bf16_f32 v37, v37, s0
	ds_write_b16 v85, v37 offset:2584
	ds_bpermute_b32 v37, v242, v125
	v_add_u32_e32 v47, 0x2000, v87
	s_waitcnt lgkmcnt(0)
	v_sub_f32_e32 v37, v37, v125
	v_mul_f32_e32 v37, 0x3fb8aa3b, v37
	v_exp_f32_e32 v37, v37
	s_nop 0
	v_mul_f32_e32 v37, v37, v46
	v_cvt_pk_bf16_f32 v37, v37, s0
	ds_write_b16 v85, v37 offset:2720
	ds_bpermute_b32 v37, v242, v127
	v_add_u32_e32 v46, 0x1800, v87
	s_waitcnt lgkmcnt(0)
	v_sub_f32_e32 v37, v37, v127
	v_mul_f32_e32 v37, 0x3fb8aa3b, v37
	v_exp_f32_e32 v37, v37
	s_nop 0
	v_mul_f32_e32 v37, v37, v45
	v_cvt_pk_bf16_f32 v37, v37, s0
	ds_write_b16 v85, v37 offset:2856
	ds_bpermute_b32 v37, v242, v138
	s_waitcnt lgkmcnt(0)
	v_sub_f32_e32 v37, v37, v138
	v_mul_f32_e32 v37, 0x3fb8aa3b, v37
	v_exp_f32_e32 v37, v37
	s_nop 0
	v_mul_f32_e32 v37, v37, v44
	v_cvt_pk_bf16_f32 v37, v37, s0
	ds_write_b16 v85, v37 offset:2992
	ds_bpermute_b32 v37, v242, v136
	s_waitcnt lgkmcnt(0)
	v_sub_f32_e32 v37, v37, v136
	v_mul_f32_e32 v37, 0x3fb8aa3b, v37
	v_exp_f32_e32 v37, v37
	s_nop 0
	v_mul_f32_e32 v37, v37, v43
	v_cvt_pk_bf16_f32 v37, v37, s0
	ds_write_b16 v85, v37 offset:3128
	ds_bpermute_b32 v37, v242, v134
	s_waitcnt lgkmcnt(0)
	v_sub_f32_e32 v37, v37, v134
	v_mul_f32_e32 v37, 0x3fb8aa3b, v37
	v_exp_f32_e32 v37, v37
	s_nop 0
	v_mul_f32_e32 v37, v37, v42
	v_cvt_pk_bf16_f32 v37, v37, s0
	ds_write_b16 v85, v37 offset:3264
	ds_bpermute_b32 v37, v242, v132
	v_add_u32_e32 v42, 0x1000, v87
	s_waitcnt lgkmcnt(0)
	v_sub_f32_e32 v37, v37, v132
	v_mul_f32_e32 v37, 0x3fb8aa3b, v37
	v_exp_f32_e32 v37, v37
	s_nop 0
	v_mul_f32_e32 v37, v37, v41
	v_cvt_pk_bf16_f32 v37, v37, s0
	ds_write_b16 v85, v37 offset:3400
	ds_bpermute_b32 v37, v242, v130
	s_waitcnt lgkmcnt(0)
	v_sub_f32_e32 v37, v37, v130
	v_mul_f32_e32 v37, 0x3fb8aa3b, v37
	v_exp_f32_e32 v37, v37
	s_nop 0
	v_mul_f32_e32 v37, v37, v40
	v_cvt_pk_bf16_f32 v37, v37, s0
	ds_write_b16 v85, v37 offset:3536
	ds_bpermute_b32 v37, v242, v128
	s_waitcnt lgkmcnt(0)
	v_sub_f32_e32 v37, v37, v128
	v_mul_f32_e32 v37, 0x3fb8aa3b, v37
	v_exp_f32_e32 v37, v37
	s_nop 0
	v_mul_f32_e32 v37, v37, v39
	v_cvt_pk_bf16_f32 v37, v37, s0
	ds_write_b16 v85, v37 offset:3672
	ds_bpermute_b32 v37, v242, v129
	s_waitcnt lgkmcnt(0)
	v_sub_f32_e32 v37, v37, v129
	v_mul_f32_e32 v37, 0x3fb8aa3b, v37
	v_exp_f32_e32 v37, v37
	s_nop 0
	v_mul_f32_e32 v37, v37, v38
	v_cvt_pk_bf16_f32 v37, v37, s0
	ds_write_b16 v85, v37 offset:3808
	ds_bpermute_b32 v37, v242, v84
	v_add_u32_e32 v38, 0x800, v87
	s_waitcnt lgkmcnt(0)
	v_sub_f32_e32 v37, v37, v84
	v_mul_f32_e32 v37, 0x3fb8aa3b, v37
	v_exp_f32_e32 v37, v37
	s_nop 0
	v_mul_f32_e32 v36, v37, v36
	v_cvt_pk_bf16_f32 v36, v36, s0
	ds_write_b16 v85, v36 offset:3944
	ds_bpermute_b32 v36, v242, v78
	s_waitcnt lgkmcnt(0)
	v_sub_f32_e32 v36, v36, v78
	v_mul_f32_e32 v36, 0x3fb8aa3b, v36
	v_exp_f32_e32 v36, v36
	s_nop 0
	v_mul_f32_e32 v35, v36, v35
	v_cvt_pk_bf16_f32 v35, v35, s0
	ds_write_b16 v85, v35 offset:4080
	ds_bpermute_b32 v35, v242, v72
	s_waitcnt lgkmcnt(0)
; #define LAS __attribute__((address_space(3)))
; #define MFMA16(a, b, c) __builtin_amdgcn_mfma_f32_16x16x32_bf16((a), (b), (c), 0, 0, 0)
; __device__ __forceinline__ void gla_stage_vt(const u32x4 (&vraw)[8], LAS bf16* VT, int lane) {
; #pragma unroll
;     for (int i = 0; i < 8; ++i) { const u32x4 w = vraw[i]; const unsigned ww[4] = {w.x, w.y, w.z, w.w};
; #pragma unroll
;         for (int e = 0; e < 4; ++e) { VT[(8 * i + 2 * e) * 68 + lane] = (bf16)(ww[e] & 0xffffu); VT[(8 * i + 2 * e + 1) * 68 + lane] = (bf16)(ww[e] >> 16); } }
; __device__ __forceinline__ void gla_local_unit(int u, const bf16* proj, const float* wg, const float* bg, float* KV, float* DEC, LAS unsigned char* wl, int lane) {
;     ...
; #pragma unroll
;     for (int ks = 0; ks < 2; ++ks) { bf16x8 a[2];
; #pragma unroll
;         for (int db = 0; db < 2; ++db) { const LAS bf16* p = KstT + (db * 16 + fr) * 68 + ks * 32 + quad * 4; a[db] = mk_frag(*(const LAS u32x2*)p, *(const LAS u32x2*)(p + 16)); }
; #pragma unroll
;         for (int vb = 0; vb < 4; ++vb) { const LAS bf16* p = VT + (vb * 16 + fr) * 68 + ks * 32 + quad * 4; const bf16x8 vf = mk_frag(*(const LAS u32x2*)p, *(const LAS u32x2*)(p + 16));
; #pragma unroll
;             for (int db = 0; db < 2; ++db) acc[db][vb] = MFMA16(a[db], vf, acc[db][vb]); } }
; #pragma unroll
;     for (int db = 0; db < 2; ++db)
; #pragma unroll
;         for (int vb = 0; vb < 4; ++vb)
; #pragma unroll
;             for (int j = 0; j < 4; ++j) KV[((size_t)u * 32 + db * 16 + quad * 4 + j) * 64 + vb * 16 + fr] = acc[db][vb][j];
	v_sub_f32_e32 v35, v35, v72
	v_mul_f32_e32 v35, 0x3fb8aa3b, v35
	v_exp_f32_e32 v35, v35
	s_nop 0
	v_mul_f32_e32 v34, v35, v34
	v_cvt_pk_bf16_f32 v34, v34, s0
	ds_write_b16 v85, v34 offset:4216
	ds_write_b16 v85, v30 offset:4352
	ds_write_b16_d16_hi v85, v30 offset:4488
	ds_write_b16 v85, v31 offset:4624
	ds_write_b16_d16_hi v85, v31 offset:4760
	ds_write_b16 v85, v32 offset:4896
	ds_write_b16_d16_hi v85, v32 offset:5032
	ds_write_b16 v85, v33 offset:5168
	ds_write_b16_d16_hi v85, v33 offset:5304
	ds_write_b16 v85, v26 offset:5440
	ds_write_b16_d16_hi v85, v26 offset:5576
	ds_write_b16 v85, v27 offset:5712
	ds_write_b16_d16_hi v85, v27 offset:5848
	ds_write_b16 v85, v28 offset:5984
	ds_write_b16_d16_hi v85, v28 offset:6120
	ds_write_b16 v85, v29 offset:6256
	ds_write_b16_d16_hi v85, v29 offset:6392
	ds_write_b16 v85, v22 offset:6528
	ds_write_b16_d16_hi v85, v22 offset:6664
	ds_write_b16 v85, v23 offset:6800
	ds_write_b16_d16_hi v85, v23 offset:6936
	ds_write_b16 v85, v24 offset:7072
	ds_write_b16_d16_hi v85, v24 offset:7208
	ds_write_b16 v85, v25 offset:7344
	ds_write_b16_d16_hi v85, v25 offset:7480
	ds_write_b16 v85, v18 offset:7616
	ds_write_b16_d16_hi v85, v18 offset:7752
	ds_write_b16 v85, v19 offset:7888
	ds_write_b16_d16_hi v85, v19 offset:8024
	ds_write_b16 v85, v20 offset:8160
	ds_write_b16_d16_hi v85, v20 offset:8296
	ds_write_b16 v85, v21 offset:8432
	ds_write_b16_d16_hi v85, v21 offset:8568
	ds_write_b16 v85, v14 offset:8704
	ds_write_b16_d16_hi v85, v14 offset:8840
	ds_write_b16 v85, v15 offset:8976
	ds_write_b16_d16_hi v85, v15 offset:9112
	ds_write_b16 v85, v16 offset:9248
	ds_write_b16_d16_hi v85, v16 offset:9384
	ds_write_b16 v85, v17 offset:9520
	ds_write_b16_d16_hi v85, v17 offset:9656
	ds_write_b16 v85, v10 offset:9792
	ds_write_b16_d16_hi v85, v10 offset:9928
	ds_write_b16 v85, v11 offset:10064
	ds_write_b16_d16_hi v85, v11 offset:10200
	ds_write_b16 v85, v12 offset:10336
	ds_write_b16_d16_hi v85, v12 offset:10472
	ds_write_b16 v85, v13 offset:10608
	ds_write_b16_d16_hi v85, v13 offset:10744
	ds_write_b16 v85, v6 offset:10880
	ds_write_b16_d16_hi v85, v6 offset:11016
	ds_write_b16 v85, v7 offset:11152
	ds_write_b16_d16_hi v85, v7 offset:11288
	ds_write_b16 v85, v8 offset:11424
	ds_write_b16_d16_hi v85, v8 offset:11560
	ds_write_b16 v85, v9 offset:11696
	ds_write_b16_d16_hi v85, v9 offset:11832
	ds_write_b16 v85, v2 offset:11968
	ds_write_b16_d16_hi v85, v2 offset:12104
	ds_write_b16 v85, v3 offset:12240
	ds_write_b16_d16_hi v85, v3 offset:12376
	ds_write_b16 v85, v4 offset:12512
	ds_write_b16_d16_hi v85, v4 offset:12648
	ds_write_b16 v85, v5 offset:12784
	ds_write_b16_d16_hi v85, v5 offset:12920
	s_waitcnt lgkmcnt(0)
	ds_read2_b64 v[2:5], v87 offset1:4
	ds_read2_b64 v[6:9], v38 offset0:16 offset1:20
	ds_read2_b64 v[10:13], v42 offset0:32 offset1:36
	ds_read2_b64 v[18:21], v46 offset0:48 offset1:52
	ds_read2_b64 v[26:29], v47 offset0:64 offset1:68
	ds_read2_b64 v[34:37], v48 offset0:32 offset1:36
	s_waitcnt lgkmcnt(3)
	v_mfma_f32_16x16x32_bf16 v[14:17], v[2:5], v[10:13], 0
	v_mfma_f32_16x16x32_bf16 v[10:13], v[6:9], v[10:13], 0
	s_waitcnt lgkmcnt(2)
	v_mfma_f32_16x16x32_bf16 v[22:25], v[2:5], v[18:21], 0
	v_mfma_f32_16x16x32_bf16 v[18:21], v[6:9], v[18:21], 0
	s_waitcnt lgkmcnt(1)
	v_mfma_f32_16x16x32_bf16 v[30:33], v[2:5], v[26:29], 0
	v_mfma_f32_16x16x32_bf16 v[26:29], v[6:9], v[26:29], 0
	s_waitcnt lgkmcnt(0)
	v_mfma_f32_16x16x32_bf16 v[2:5], v[2:5], v[34:37], 0
	v_mfma_f32_16x16x32_bf16 v[6:9], v[6:9], v[34:37], 0
	ds_read2_b64 v[34:37], v87 offset0:8 offset1:12
	ds_read2_b64 v[38:41], v38 offset0:24 offset1:28
	ds_read2_b64 v[42:45], v42 offset0:40 offset1:44
	s_waitcnt lgkmcnt(0)
	v_mfma_f32_16x16x32_bf16 v[14:17], v[34:37], v[42:45], v[14:17]
	v_mfma_f32_16x16x32_bf16 v[10:13], v[38:41], v[42:45], v[10:13]
	ds_read2_b64 v[42:45], v46 offset0:56 offset1:60
	s_waitcnt lgkmcnt(0)
	v_mfma_f32_16x16x32_bf16 v[22:25], v[34:37], v[42:45], v[22:25]
	v_mfma_f32_16x16x32_bf16 v[18:21], v[38:41], v[42:45], v[18:21]
	ds_read2_b64 v[42:45], v47 offset0:72 offset1:76
	s_waitcnt lgkmcnt(0)
	v_mfma_f32_16x16x32_bf16 v[30:33], v[34:37], v[42:45], v[30:33]
	v_mfma_f32_16x16x32_bf16 v[26:29], v[38:41], v[42:45], v[26:29]
	ds_read2_b64 v[42:45], v48 offset0:40 offset1:44
	s_waitcnt lgkmcnt(0)
	v_mfma_f32_16x16x32_bf16 v[2:5], v[34:37], v[42:45], v[2:5]
	global_store_dword v[62:63], v14, off
	global_store_dword v[62:63], v15, off offset:256
	global_store_dword v[62:63], v16, off offset:512
	global_store_dword v[62:63], v17, off offset:768
	global_store_dword v[62:63], v22, off offset:64
	global_store_dword v[62:63], v23, off offset:320
	global_store_dword v[62:63], v24, off offset:576
	global_store_dword v[62:63], v25, off offset:832
	global_store_dword v[62:63], v30, off offset:128
	global_store_dword v[62:63], v31, off offset:384
	global_store_dword v[62:63], v32, off offset:640
	global_store_dword v[62:63], v33, off offset:896
	global_store_dword v[62:63], v2, off offset:192
	global_store_dword v[62:63], v3, off offset:448
	global_store_dword v[62:63], v4, off offset:704
	global_store_dword v[62:63], v5, off offset:960
	v_add_co_u32_e32 v2, vcc, s39, v62
	v_mfma_f32_16x16x32_bf16 v[6:9], v[38:41], v[42:45], v[6:9]
	s_nop 0
	v_addc_co_u32_e32 v3, vcc, 0, v63, vcc
	global_store_dword v[2:3], v10, off
	global_store_dword v[2:3], v11, off offset:256
	global_store_dword v[2:3], v12, off offset:512
	global_store_dword v[2:3], v13, off offset:768
	global_store_dword v[2:3], v18, off offset:64
	global_store_dword v[2:3], v19, off offset:320
	global_store_dword v[2:3], v20, off offset:576
	global_store_dword v[2:3], v21, off offset:832
	global_store_dword v[2:3], v26, off offset:128
	global_store_dword v[2:3], v27, off offset:384
	global_store_dword v[2:3], v28, off offset:640
	global_store_dword v[2:3], v29, off offset:896
	global_store_dword v[2:3], v6, off offset:192
	global_store_dword v[2:3], v7, off offset:448
	global_store_dword v[2:3], v8, off offset:704
	global_store_dword v[2:3], v9, off offset:960
	s_and_saveexec_b64 s[18:19], s[16:17]
	s_cbranch_execz .LBB0_436
; __device__ __forceinline__ void gla_local_unit(int u, const bf16* proj, const float* wg, const float* bg, float* KV, float* DEC, LAS unsigned char* wl, int lane) {
;     ...
;     if (lane == 63) {
; #pragma unroll
;         for (int d = 0; d < 32; ++d) DEC[u * 32 + d] = __expf(bc[d]); }
	v_mul_f32_e32 v2, 0x3fb8aa3b, v50
	v_mul_f32_e32 v3, 0x3fb8aa3b, v51
	v_mul_f32_e32 v4, 0x3fb8aa3b, v52
	v_mul_f32_e32 v5, 0x3fb8aa3b, v53
	v_exp_f32_e32 v2, v2
	s_ashr_i32 s71, s70, 31
	v_exp_f32_e32 v3, v3
	v_exp_f32_e32 v4, v4
	v_exp_f32_e32 v5, v5
	s_lshl_b64 s[2:3], s[70:71], 2
	s_add_u32 s74, s76, s2
	s_addc_u32 s75, s77, s3
	global_store_dwordx4 v1, v[2:5], s[74:75]
	s_nop 1
	v_mul_f32_e32 v2, 0x3fb8aa3b, v54
	v_mul_f32_e32 v3, 0x3fb8aa3b, v55
	v_mul_f32_e32 v4, 0x3fb8aa3b, v64
	v_mul_f32_e32 v5, 0x3fb8aa3b, v66
	v_exp_f32_e32 v2, v2
	v_exp_f32_e32 v3, v3
	v_exp_f32_e32 v4, v4
	v_exp_f32_e32 v5, v5
	global_store_dwordx4 v1, v[2:5], s[74:75] offset:16
	s_nop 1
	v_mul_f32_e32 v2, 0x3fb8aa3b, v68
	v_mul_f32_e32 v3, 0x3fb8aa3b, v60
	v_mul_f32_e32 v4, 0x3fb8aa3b, v58
	v_mul_f32_e32 v5, 0x3fb8aa3b, v56
	v_exp_f32_e32 v2, v2
	v_exp_f32_e32 v3, v3
	v_exp_f32_e32 v4, v4
	v_exp_f32_e32 v5, v5
	global_store_dwordx4 v1, v[2:5], s[74:75] offset:32
	s_nop 1
	v_mul_f32_e32 v2, 0x3fb8aa3b, v57
	v_mul_f32_e32 v3, 0x3fb8aa3b, v59
	v_mul_f32_e32 v4, 0x3fb8aa3b, v61
	v_mul_f32_e32 v5, 0x3fb8aa3b, v86
	v_exp_f32_e32 v2, v2
	v_exp_f32_e32 v3, v3
	v_exp_f32_e32 v4, v4
	v_exp_f32_e32 v5, v5
	global_store_dwordx4 v1, v[2:5], s[74:75] offset:48
	s_nop 1
	v_mul_f32_e32 v2, 0x3fb8aa3b, v91
	v_mul_f32_e32 v3, 0x3fb8aa3b, v96
	v_mul_f32_e32 v4, 0x3fb8aa3b, v97
	v_mul_f32_e32 v5, 0x3fb8aa3b, v104
	v_exp_f32_e32 v2, v2
	v_exp_f32_e32 v3, v3
	v_exp_f32_e32 v4, v4
	v_exp_f32_e32 v5, v5
	global_store_dwordx4 v1, v[2:5], s[74:75] offset:64
	s_nop 1
	v_mul_f32_e32 v2, 0x3fb8aa3b, v107
	v_mul_f32_e32 v3, 0x3fb8aa3b, v109
	v_mul_f32_e32 v4, 0x3fb8aa3b, v112
	v_mul_f32_e32 v5, 0x3fb8aa3b, v113
	v_exp_f32_e32 v2, v2
	v_exp_f32_e32 v3, v3
	v_exp_f32_e32 v4, v4
	v_exp_f32_e32 v5, v5
	global_store_dwordx4 v1, v[2:5], s[74:75] offset:80
	s_nop 1
	v_mul_f32_e32 v2, 0x3fb8aa3b, v114
	v_mul_f32_e32 v3, 0x3fb8aa3b, v115
	v_mul_f32_e32 v4, 0x3fb8aa3b, v117
	v_mul_f32_e32 v5, 0x3fb8aa3b, v123
	v_exp_f32_e32 v2, v2
	v_exp_f32_e32 v3, v3
	v_exp_f32_e32 v4, v4
	v_exp_f32_e32 v5, v5
	global_store_dwordx4 v1, v[2:5], s[74:75] offset:96
	s_nop 1
	v_mul_f32_e32 v2, 0x3fb8aa3b, v103
	v_mul_f32_e32 v3, 0x3fb8aa3b, v82
	v_mul_f32_e32 v4, 0x3fb8aa3b, v76
	v_mul_f32_e32 v5, 0x3fb8aa3b, v70
	v_exp_f32_e32 v2, v2
	v_exp_f32_e32 v3, v3
	v_exp_f32_e32 v4, v4
	v_exp_f32_e32 v5, v5
	global_store_dwordx4 v1, v[2:5], s[74:75] offset:112
	s_branch .LBB0_436
